# SSD conv+silu rewritten by hand with packed f32 (v_pk_fma/mul/add) on column pairs, same op order and numerics
# baseline (speedup 1.0000x reference)
; __device__ __forceinline__ float bflo(unsigned u) { return __uint_as_float(u << 16); }
; __device__ __forceinline__ float bfhi(unsigned u) { return __uint_as_float(u & 0xffff0000u); }
; __device__ __forceinline__ void ssd_item(const Params& p, LAS unsigned char* lds, int bl, int head, int dry) {
;     ...
;             if (c == 0 && rg == 0) { raw[0] = (u32x2){0u, 0u}; raw[1] = (u32x2){0u, 0u}; raw[2] = (u32x2){0u, 0u}; }
; #pragma unroll
;             for (int seg = 0; seg < 4; ++seg) {
;                 float val[8][4];
; #pragma unroll
;                 for (int j = 0; j < 8; ++j) { const int i = seg * 8 + j;
;                     const u32x2 x0 = raw[i], x1 = raw[i + 1], x2 = raw[i + 2], x3 = raw[i + 3];
;                     float v0 = cbv[0] + cw0[0] * bflo(x0.x) + cw1[0] * bflo(x1.x) + cw2[0] * bflo(x2.x) + cw3[0] * bflo(x3.x);
;                     float v1 = cbv[1] + cw0[1] * bfhi(x0.x) + cw1[1] * bfhi(x1.x) + cw2[1] * bfhi(x2.x) + cw3[1] * bfhi(x3.x);
;                     float v2 = cbv[2] + cw0[2] * bflo(x0.y) + cw1[2] * bflo(x1.y) + cw2[2] * bflo(x2.y) + cw3[2] * bflo(x3.y);
;                     float v3 = cbv[3] + cw0[3] * bfhi(x0.y) + cw1[3] * bfhi(x1.y) + cw2[3] * bfhi(x2.y) + cw3[3] * bfhi(x3.y);
.Lcw_skip:
	v_mov_b32_e32 v214, 0xbfb8aa3b
	v_mov_b32_e32 v215, 0xbfb8aa3b
	v_mov_b32_e32 v216, 1.0
	v_mov_b32_e32 v217, 1.0
	v_add_u32_e32 v218, s63, v182
	v_lshl_add_u32 v218, v170, 2, v218
	v_or_b32_e32 v194, s58, v166
	v_cmp_eq_u32_e32 vcc, 0, v194
	s_waitcnt vmcnt(37)
	s_nop 0
	v_cndmask_b32_e64 v150, v150, 0, vcc
	v_cndmask_b32_e64 v151, v151, 0, vcc
	v_cndmask_b32_e64 v152, v152, 0, vcc
	v_cndmask_b32_e64 v153, v153, 0, vcc
	v_cndmask_b32_e64 v154, v154, 0, vcc
	v_cndmask_b32_e64 v155, v155, 0, vcc
	v_lshlrev_b32_e32 v194, 16, v150
	v_and_b32_e32 v195, 0xffff0000, v150
	v_lshlrev_b32_e32 v196, 16, v151
	v_and_b32_e32 v197, 0xffff0000, v151
	v_pk_fma_f32 v[16:17], v[48:49], v[194:195], v[64:65]
	v_pk_fma_f32 v[18:19], v[50:51], v[196:197], v[66:67]
	v_lshlrev_b32_e32 v198, 16, v152
	v_and_b32_e32 v199, 0xffff0000, v152
	v_lshlrev_b32_e32 v200, 16, v153
	v_and_b32_e32 v201, 0xffff0000, v153
	v_pk_fma_f32 v[20:21], v[48:49], v[198:199], v[64:65]
	v_pk_fma_f32 v[22:23], v[50:51], v[200:201], v[66:67]
	v_pk_fma_f32 v[16:17], v[52:53], v[198:199], v[16:17]
	v_pk_fma_f32 v[18:19], v[54:55], v[200:201], v[18:19]
	v_lshlrev_b32_e32 v194, 16, v154
	v_and_b32_e32 v195, 0xffff0000, v154
	v_lshlrev_b32_e32 v196, 16, v155
	v_and_b32_e32 v197, 0xffff0000, v155
	v_pk_fma_f32 v[24:25], v[48:49], v[194:195], v[64:65]
	v_pk_fma_f32 v[26:27], v[50:51], v[196:197], v[66:67]
	v_pk_fma_f32 v[20:21], v[52:53], v[194:195], v[20:21]
	v_pk_fma_f32 v[22:23], v[54:55], v[196:197], v[22:23]
	v_pk_fma_f32 v[16:17], v[56:57], v[194:195], v[16:17]
	v_pk_fma_f32 v[18:19], v[58:59], v[196:197], v[18:19]
	v_lshlrev_b32_e32 v198, 16, v148
	v_and_b32_e32 v199, 0xffff0000, v148
	v_lshlrev_b32_e32 v200, 16, v149
	v_and_b32_e32 v201, 0xffff0000, v149
	v_pk_fma_f32 v[28:29], v[48:49], v[198:199], v[64:65]
	v_pk_fma_f32 v[30:31], v[50:51], v[200:201], v[66:67]
	v_pk_fma_f32 v[24:25], v[52:53], v[198:199], v[24:25]
	v_pk_fma_f32 v[26:27], v[54:55], v[200:201], v[26:27]
	v_pk_fma_f32 v[20:21], v[56:57], v[198:199], v[20:21]
	v_pk_fma_f32 v[22:23], v[58:59], v[200:201], v[22:23]
	v_pk_fma_f32 v[16:17], v[60:61], v[198:199], v[16:17]
	v_pk_fma_f32 v[18:19], v[62:63], v[200:201], v[18:19]
	s_waitcnt vmcnt(36)
	v_lshlrev_b32_e32 v194, 16, v146
	v_and_b32_e32 v195, 0xffff0000, v146
	v_lshlrev_b32_e32 v196, 16, v147
	v_and_b32_e32 v197, 0xffff0000, v147
	v_pk_fma_f32 v[32:33], v[48:49], v[194:195], v[64:65]
	v_pk_fma_f32 v[34:35], v[50:51], v[196:197], v[66:67]
	v_pk_fma_f32 v[28:29], v[52:53], v[194:195], v[28:29]
	v_pk_fma_f32 v[30:31], v[54:55], v[196:197], v[30:31]
	v_pk_fma_f32 v[24:25], v[56:57], v[194:195], v[24:25]
	v_pk_fma_f32 v[26:27], v[58:59], v[196:197], v[26:27]
	v_pk_fma_f32 v[20:21], v[60:61], v[194:195], v[20:21]
	v_pk_fma_f32 v[22:23], v[62:63], v[196:197], v[22:23]
	s_waitcnt vmcnt(35)
	v_lshlrev_b32_e32 v198, 16, v144
	v_and_b32_e32 v199, 0xffff0000, v144
	v_lshlrev_b32_e32 v200, 16, v145
	v_and_b32_e32 v201, 0xffff0000, v145
	v_pk_fma_f32 v[36:37], v[48:49], v[198:199], v[64:65]
	v_pk_fma_f32 v[38:39], v[50:51], v[200:201], v[66:67]
	v_pk_fma_f32 v[32:33], v[52:53], v[198:199], v[32:33]
	v_pk_fma_f32 v[34:35], v[54:55], v[200:201], v[34:35]
	v_pk_fma_f32 v[28:29], v[56:57], v[198:199], v[28:29]
	v_pk_fma_f32 v[30:31], v[58:59], v[200:201], v[30:31]
	v_pk_fma_f32 v[24:25], v[60:61], v[198:199], v[24:25]
	v_pk_fma_f32 v[26:27], v[62:63], v[200:201], v[26:27]
	s_waitcnt vmcnt(34)
	v_lshlrev_b32_e32 v194, 16, v142
	v_and_b32_e32 v195, 0xffff0000, v142
	v_lshlrev_b32_e32 v196, 16, v143
	v_and_b32_e32 v197, 0xffff0000, v143
	v_pk_fma_f32 v[40:41], v[48:49], v[194:195], v[64:65]
	v_pk_fma_f32 v[42:43], v[50:51], v[196:197], v[66:67]
	v_pk_fma_f32 v[36:37], v[52:53], v[194:195], v[36:37]
	v_pk_fma_f32 v[38:39], v[54:55], v[196:197], v[38:39]
	v_pk_fma_f32 v[32:33], v[56:57], v[194:195], v[32:33]
	v_pk_fma_f32 v[34:35], v[58:59], v[196:197], v[34:35]
	v_pk_fma_f32 v[28:29], v[60:61], v[194:195], v[28:29]
	v_pk_fma_f32 v[30:31], v[62:63], v[196:197], v[30:31]
	s_waitcnt vmcnt(33)
	v_lshlrev_b32_e32 v198, 16, v140
	v_and_b32_e32 v199, 0xffff0000, v140
	v_lshlrev_b32_e32 v200, 16, v141
	v_and_b32_e32 v201, 0xffff0000, v141
	v_pk_fma_f32 v[44:45], v[48:49], v[198:199], v[64:65]
	v_pk_fma_f32 v[46:47], v[50:51], v[200:201], v[66:67]
	v_pk_fma_f32 v[40:41], v[52:53], v[198:199], v[40:41]
	v_pk_fma_f32 v[42:43], v[54:55], v[200:201], v[42:43]
	v_pk_fma_f32 v[36:37], v[56:57], v[198:199], v[36:37]
	v_pk_fma_f32 v[38:39], v[58:59], v[200:201], v[38:39]
	v_pk_fma_f32 v[32:33], v[60:61], v[198:199], v[32:33]
	v_pk_fma_f32 v[34:35], v[62:63], v[200:201], v[34:35]
	s_waitcnt vmcnt(32)
	v_lshlrev_b32_e32 v194, 16, v138
	v_and_b32_e32 v195, 0xffff0000, v138
	v_lshlrev_b32_e32 v196, 16, v139
	v_and_b32_e32 v197, 0xffff0000, v139
	v_pk_fma_f32 v[44:45], v[52:53], v[194:195], v[44:45]
	v_pk_fma_f32 v[46:47], v[54:55], v[196:197], v[46:47]
	v_pk_fma_f32 v[40:41], v[56:57], v[194:195], v[40:41]
	v_pk_fma_f32 v[42:43], v[58:59], v[196:197], v[42:43]
	v_pk_fma_f32 v[36:37], v[60:61], v[194:195], v[36:37]
	v_pk_fma_f32 v[38:39], v[62:63], v[196:197], v[38:39]
	s_waitcnt vmcnt(31)
	v_lshlrev_b32_e32 v198, 16, v136
	v_and_b32_e32 v199, 0xffff0000, v136
	v_lshlrev_b32_e32 v200, 16, v137
	v_and_b32_e32 v201, 0xffff0000, v137
	v_pk_fma_f32 v[44:45], v[56:57], v[198:199], v[44:45]
	v_pk_fma_f32 v[46:47], v[58:59], v[200:201], v[46:47]
	v_pk_fma_f32 v[40:41], v[60:61], v[198:199], v[40:41]
	v_pk_fma_f32 v[42:43], v[62:63], v[200:201], v[42:43]
	s_waitcnt vmcnt(30)
; __device__ __forceinline__ unsigned cvt_pk_bf16(float lo, float hi) { unsigned r; asm volatile("v_cvt_pk_bf16_f32 %0, %1, %2" : "=v"(r) : "v"(lo), "v"(hi)); return r; }
; #define LAS __attribute__((address_space(3)))
; __device__ __forceinline__ float bflo(unsigned u) { return __uint_as_float(u << 16); }
; __device__ __forceinline__ float bfhi(unsigned u) { return __uint_as_float(u & 0xffff0000u); }
; __device__ __forceinline__ float siluf_(float v) { return v * __builtin_amdgcn_rcpf(1.0f + __expf(-v)); }
; __device__ __forceinline__ void ssd_item(const Params& p, LAS unsigned char* lds, int bl, int head, int dry) {
;     ...
;                 for (int j = 0; j < 8; ++j) { const int i = seg * 8 + j;
;                     const u32x2 x0 = raw[i], x1 = raw[i + 1], x2 = raw[i + 2], x3 = raw[i + 3];
;                     float v0 = cbv[0] + cw0[0] * bflo(x0.x) + cw1[0] * bflo(x1.x) + cw2[0] * bflo(x2.x) + cw3[0] * bflo(x3.x);
;                     float v1 = cbv[1] + cw0[1] * bfhi(x0.x) + cw1[1] * bfhi(x1.x) + cw2[1] * bfhi(x2.x) + cw3[1] * bfhi(x3.x);
;                     float v2 = cbv[2] + cw0[2] * bflo(x0.y) + cw1[2] * bflo(x1.y) + cw2[2] * bflo(x2.y) + cw3[2] * bflo(x3.y);
;                     float v3 = cbv[3] + cw0[3] * bfhi(x0.y) + cw1[3] * bfhi(x1.y) + cw2[3] * bfhi(x2.y) + cw3[3] * bfhi(x3.y);
;                     val[j][0] = siluf_(v0); val[j][1] = siluf_(v1); val[j][2] = siluf_(v2); val[j][3] = siluf_(v3); }
;                 const int lb = rg * 32 + seg * 8;
;                 if (kind != 0) { LAS bf16_t* rm = (kind == 1 ? BMm : CM) + lb * SLD + n4;
; #pragma unroll
;                     for (int j = 0; j < 8; ++j) { u32x2 o; o.x = cvt_pk_bf16(val[j][0], val[j][1]); o.y = cvt_pk_bf16(val[j][2], val[j][3]); *(LAS u32x2*)(rm + j * SLD) = o; } }
	v_lshlrev_b32_e32 v194, 16, v134
	v_and_b32_e32 v195, 0xffff0000, v134
	v_lshlrev_b32_e32 v196, 16, v135
	v_and_b32_e32 v197, 0xffff0000, v135
	v_pk_fma_f32 v[44:45], v[60:61], v[194:195], v[44:45]
	v_pk_fma_f32 v[46:47], v[62:63], v[196:197], v[46:47]
	v_pk_mul_f32 v[202:203], v[16:17], v[214:215]
	v_pk_mul_f32 v[204:205], v[18:19], v[214:215]
	v_exp_f32_e32 v202, v202
	v_exp_f32_e32 v203, v203
	v_exp_f32_e32 v204, v204
	v_exp_f32_e32 v205, v205
	v_pk_add_f32 v[202:203], v[202:203], v[216:217]
	v_pk_add_f32 v[204:205], v[204:205], v[216:217]
	v_rcp_f32_e32 v202, v202
	v_rcp_f32_e32 v203, v203
	v_rcp_f32_e32 v204, v204
	v_rcp_f32_e32 v205, v205
	v_pk_mul_f32 v[16:17], v[16:17], v[202:203]
	v_pk_mul_f32 v[18:19], v[18:19], v[204:205]
	v_pk_mul_f32 v[202:203], v[20:21], v[214:215]
	v_pk_mul_f32 v[204:205], v[22:23], v[214:215]
	v_exp_f32_e32 v202, v202
	v_exp_f32_e32 v203, v203
	v_exp_f32_e32 v204, v204
	v_exp_f32_e32 v205, v205
	v_pk_add_f32 v[202:203], v[202:203], v[216:217]
	v_pk_add_f32 v[204:205], v[204:205], v[216:217]
	v_rcp_f32_e32 v202, v202
	v_rcp_f32_e32 v203, v203
	v_rcp_f32_e32 v204, v204
	v_rcp_f32_e32 v205, v205
	v_pk_mul_f32 v[20:21], v[20:21], v[202:203]
	v_pk_mul_f32 v[22:23], v[22:23], v[204:205]
	v_pk_mul_f32 v[202:203], v[24:25], v[214:215]
	v_pk_mul_f32 v[204:205], v[26:27], v[214:215]
	v_exp_f32_e32 v202, v202
	v_exp_f32_e32 v203, v203
	v_exp_f32_e32 v204, v204
	v_exp_f32_e32 v205, v205
	v_pk_add_f32 v[202:203], v[202:203], v[216:217]
	v_pk_add_f32 v[204:205], v[204:205], v[216:217]
	v_rcp_f32_e32 v202, v202
	v_rcp_f32_e32 v203, v203
	v_rcp_f32_e32 v204, v204
	v_rcp_f32_e32 v205, v205
	v_pk_mul_f32 v[24:25], v[24:25], v[202:203]
	v_pk_mul_f32 v[26:27], v[26:27], v[204:205]
	v_pk_mul_f32 v[202:203], v[28:29], v[214:215]
	v_pk_mul_f32 v[204:205], v[30:31], v[214:215]
	v_exp_f32_e32 v202, v202
	v_exp_f32_e32 v203, v203
	v_exp_f32_e32 v204, v204
	v_exp_f32_e32 v205, v205
	v_pk_add_f32 v[202:203], v[202:203], v[216:217]
	v_pk_add_f32 v[204:205], v[204:205], v[216:217]
	v_rcp_f32_e32 v202, v202
	v_rcp_f32_e32 v203, v203
	v_rcp_f32_e32 v204, v204
	v_rcp_f32_e32 v205, v205
	v_pk_mul_f32 v[28:29], v[28:29], v[202:203]
	v_pk_mul_f32 v[30:31], v[30:31], v[204:205]
	v_pk_mul_f32 v[202:203], v[32:33], v[214:215]
	v_pk_mul_f32 v[204:205], v[34:35], v[214:215]
	v_exp_f32_e32 v202, v202
	v_exp_f32_e32 v203, v203
	v_exp_f32_e32 v204, v204
	v_exp_f32_e32 v205, v205
	v_pk_add_f32 v[202:203], v[202:203], v[216:217]
	v_pk_add_f32 v[204:205], v[204:205], v[216:217]
	v_rcp_f32_e32 v202, v202
	v_rcp_f32_e32 v203, v203
	v_rcp_f32_e32 v204, v204
	v_rcp_f32_e32 v205, v205
	v_pk_mul_f32 v[32:33], v[32:33], v[202:203]
	v_pk_mul_f32 v[34:35], v[34:35], v[204:205]
	v_pk_mul_f32 v[202:203], v[36:37], v[214:215]
	v_pk_mul_f32 v[204:205], v[38:39], v[214:215]
	v_exp_f32_e32 v202, v202
	v_exp_f32_e32 v203, v203
	v_exp_f32_e32 v204, v204
	v_exp_f32_e32 v205, v205
	v_pk_add_f32 v[202:203], v[202:203], v[216:217]
	v_pk_add_f32 v[204:205], v[204:205], v[216:217]
	v_rcp_f32_e32 v202, v202
	v_rcp_f32_e32 v203, v203
	v_rcp_f32_e32 v204, v204
	v_rcp_f32_e32 v205, v205
	v_pk_mul_f32 v[36:37], v[36:37], v[202:203]
	v_pk_mul_f32 v[38:39], v[38:39], v[204:205]
	v_pk_mul_f32 v[202:203], v[40:41], v[214:215]
	v_pk_mul_f32 v[204:205], v[42:43], v[214:215]
	v_exp_f32_e32 v202, v202
	v_exp_f32_e32 v203, v203
	v_exp_f32_e32 v204, v204
	v_exp_f32_e32 v205, v205
	v_pk_add_f32 v[202:203], v[202:203], v[216:217]
	v_pk_add_f32 v[204:205], v[204:205], v[216:217]
	v_rcp_f32_e32 v202, v202
	v_rcp_f32_e32 v203, v203
	v_rcp_f32_e32 v204, v204
	v_rcp_f32_e32 v205, v205
	v_pk_mul_f32 v[40:41], v[40:41], v[202:203]
	v_pk_mul_f32 v[42:43], v[42:43], v[204:205]
	v_pk_mul_f32 v[202:203], v[44:45], v[214:215]
	v_pk_mul_f32 v[204:205], v[46:47], v[214:215]
	v_exp_f32_e32 v202, v202
	v_exp_f32_e32 v203, v203
	v_exp_f32_e32 v204, v204
	v_exp_f32_e32 v205, v205
	v_pk_add_f32 v[202:203], v[202:203], v[216:217]
	v_pk_add_f32 v[204:205], v[204:205], v[216:217]
	v_rcp_f32_e32 v202, v202
	v_rcp_f32_e32 v203, v203
	v_rcp_f32_e32 v204, v204
	v_rcp_f32_e32 v205, v205
	v_pk_mul_f32 v[44:45], v[44:45], v[202:203]
	v_pk_mul_f32 v[46:47], v[46:47], v[204:205]
	s_and_saveexec_b64 vcc, s[38:39]
	s_cbranch_execz .Lcv_rm_0
	v_cvt_pk_bf16_f32 v194, v16, v17
	v_cvt_pk_bf16_f32 v195, v18, v19
	ds_write_b64 v187, v[194:195]
	v_cvt_pk_bf16_f32 v196, v20, v21
	v_cvt_pk_bf16_f32 v197, v22, v23
	ds_write_b64 v187, v[196:197] offset:272
	v_cvt_pk_bf16_f32 v194, v24, v25
	v_cvt_pk_bf16_f32 v195, v26, v27
	ds_write_b64 v187, v[194:195] offset:544
	v_cvt_pk_bf16_f32 v196, v28, v29
	v_cvt_pk_bf16_f32 v197, v30, v31
	ds_write_b64 v187, v[196:197] offset:816
	v_cvt_pk_bf16_f32 v194, v32, v33
	v_cvt_pk_bf16_f32 v195, v34, v35
	ds_write_b64 v187, v[194:195] offset:1088
	v_cvt_pk_bf16_f32 v196, v36, v37
	v_cvt_pk_bf16_f32 v197, v38, v39
	ds_write_b64 v187, v[196:197] offset:1360
	v_cvt_pk_bf16_f32 v194, v40, v41
	v_cvt_pk_bf16_f32 v195, v42, v43
	ds_write_b64 v187, v[194:195] offset:1632
	v_cvt_pk_bf16_f32 v196, v44, v45
	v_cvt_pk_bf16_f32 v197, v46, v47
	ds_write_b64 v187, v[196:197] offset:1904
; __device__ __forceinline__ unsigned cvt_pk_bf16(float lo, float hi) { unsigned r; asm volatile("v_cvt_pk_bf16_f32 %0, %1, %2" : "=v"(r) : "v"(lo), "v"(hi)); return r; }
; #define LAS __attribute__((address_space(3)))
; __device__ __forceinline__ float bflo(unsigned u) { return __uint_as_float(u << 16); }
; __device__ __forceinline__ float bfhi(unsigned u) { return __uint_as_float(u & 0xffff0000u); }
; __device__ __forceinline__ void ssd_item(const Params& p, LAS unsigned char* lds, int bl, int head, int dry) {
;     ...
;                 for (int j = 0; j < 8; ++j) { const int i = seg * 8 + j;
;                     const u32x2 x0 = raw[i], x1 = raw[i + 1], x2 = raw[i + 2], x3 = raw[i + 3];
;                     float v0 = cbv[0] + cw0[0] * bflo(x0.x) + cw1[0] * bflo(x1.x) + cw2[0] * bflo(x2.x) + cw3[0] * bflo(x3.x);
;                     float v1 = cbv[1] + cw0[1] * bfhi(x0.x) + cw1[1] * bfhi(x1.x) + cw2[1] * bfhi(x2.x) + cw3[1] * bfhi(x3.x);
;                     float v2 = cbv[2] + cw0[2] * bflo(x0.y) + cw1[2] * bflo(x1.y) + cw2[2] * bflo(x2.y) + cw3[2] * bflo(x3.y);
;                     float v3 = cbv[3] + cw0[3] * bfhi(x0.y) + cw1[3] * bfhi(x1.y) + cw2[3] * bfhi(x2.y) + cw3[3] * bfhi(x3.y);
;     ...
;                 if (kind != 2) { LAS float* sc = (kind == 0 ? fdt : fwl) + lb; LAS bf16_t* tp = (kind == 0 ? XT : BT) + n4 * SLD + lb;
;                     float scl[8];
; #pragma unroll
;                     for (int j = 0; j < 8; ++j) scl[j] = sc[j];
; #pragma unroll
;                     for (int e = 0; e < 4; ++e) { u32x4 o; o.x = cvt_pk_bf16(val[0][e] * scl[0], val[1][e] * scl[1]); o.y = cvt_pk_bf16(val[2][e] * scl[2], val[3][e] * scl[3]);
;                         o.z = cvt_pk_bf16(val[4][e] * scl[4], val[5][e] * scl[5]); o.w = cvt_pk_bf16(val[6][e] * scl[6], val[7][e] * scl[7]); *(LAS u32x4*)(tp + e * SLD) = o; } }
.Lcv_rm_0:
	s_or_b64 exec, exec, vcc
	s_and_saveexec_b64 vcc, s[34:35]
	s_cbranch_execz .Lcv_tr_0
	ds_read_b128 v[206:209], v218
	ds_read_b128 v[210:213], v218 offset:16
	s_waitcnt lgkmcnt(0)
	v_pk_mul_f32 v[16:17], v[16:17], v[206:207] op_sel_hi:[1,0]
	v_pk_mul_f32 v[18:19], v[18:19], v[206:207] op_sel_hi:[1,0]
	v_pk_mul_f32 v[20:21], v[20:21], v[206:207] op_sel:[0,1] op_sel_hi:[1,1]
	v_pk_mul_f32 v[22:23], v[22:23], v[206:207] op_sel:[0,1] op_sel_hi:[1,1]
	v_pk_mul_f32 v[24:25], v[24:25], v[208:209] op_sel_hi:[1,0]
	v_pk_mul_f32 v[26:27], v[26:27], v[208:209] op_sel_hi:[1,0]
	v_pk_mul_f32 v[28:29], v[28:29], v[208:209] op_sel:[0,1] op_sel_hi:[1,1]
	v_pk_mul_f32 v[30:31], v[30:31], v[208:209] op_sel:[0,1] op_sel_hi:[1,1]
	v_pk_mul_f32 v[32:33], v[32:33], v[210:211] op_sel_hi:[1,0]
	v_pk_mul_f32 v[34:35], v[34:35], v[210:211] op_sel_hi:[1,0]
	v_pk_mul_f32 v[36:37], v[36:37], v[210:211] op_sel:[0,1] op_sel_hi:[1,1]
	v_pk_mul_f32 v[38:39], v[38:39], v[210:211] op_sel:[0,1] op_sel_hi:[1,1]
	v_pk_mul_f32 v[40:41], v[40:41], v[212:213] op_sel_hi:[1,0]
	v_pk_mul_f32 v[42:43], v[42:43], v[212:213] op_sel_hi:[1,0]
	v_pk_mul_f32 v[44:45], v[44:45], v[212:213] op_sel:[0,1] op_sel_hi:[1,1]
	v_pk_mul_f32 v[46:47], v[46:47], v[212:213] op_sel:[0,1] op_sel_hi:[1,1]
	v_cvt_pk_bf16_f32 v236, v16, v20
	v_cvt_pk_bf16_f32 v237, v24, v28
	v_cvt_pk_bf16_f32 v238, v32, v36
	v_cvt_pk_bf16_f32 v239, v40, v44
	ds_write_b128 v178, v[236:239]
	v_cvt_pk_bf16_f32 v198, v17, v21
	v_cvt_pk_bf16_f32 v199, v25, v29
	v_cvt_pk_bf16_f32 v200, v33, v37
	v_cvt_pk_bf16_f32 v201, v41, v45
	ds_write_b128 v178, v[198:201] offset:272
	v_cvt_pk_bf16_f32 v236, v18, v22
	v_cvt_pk_bf16_f32 v237, v26, v30
	v_cvt_pk_bf16_f32 v238, v34, v38
	v_cvt_pk_bf16_f32 v239, v42, v46
	ds_write_b128 v178, v[236:239] offset:544
	v_cvt_pk_bf16_f32 v198, v19, v23
	v_cvt_pk_bf16_f32 v199, v27, v31
	v_cvt_pk_bf16_f32 v200, v35, v39
	v_cvt_pk_bf16_f32 v201, v43, v47
	ds_write_b128 v178, v[198:201] offset:816
.Lcv_tr_0:
	s_or_b64 exec, exec, vcc
	s_cmp_ge_u32 s98, 4
	s_cbranch_scc1 .Lconv_skip
	v_lshlrev_b32_e32 v194, 16, v138
	v_and_b32_e32 v195, 0xffff0000, v138
	v_lshlrev_b32_e32 v196, 16, v139
	v_and_b32_e32 v197, 0xffff0000, v139
	v_pk_fma_f32 v[16:17], v[48:49], v[194:195], v[64:65]
	v_pk_fma_f32 v[18:19], v[50:51], v[196:197], v[66:67]
	v_lshlrev_b32_e32 v198, 16, v136
	v_and_b32_e32 v199, 0xffff0000, v136
	v_lshlrev_b32_e32 v200, 16, v137
	v_and_b32_e32 v201, 0xffff0000, v137
	v_pk_fma_f32 v[20:21], v[48:49], v[198:199], v[64:65]
	v_pk_fma_f32 v[22:23], v[50:51], v[200:201], v[66:67]
	v_pk_fma_f32 v[16:17], v[52:53], v[198:199], v[16:17]
	v_pk_fma_f32 v[18:19], v[54:55], v[200:201], v[18:19]
	v_lshlrev_b32_e32 v194, 16, v134
	v_and_b32_e32 v195, 0xffff0000, v134
	v_lshlrev_b32_e32 v196, 16, v135
	v_and_b32_e32 v197, 0xffff0000, v135
	v_pk_fma_f32 v[24:25], v[48:49], v[194:195], v[64:65]
	v_pk_fma_f32 v[26:27], v[50:51], v[196:197], v[66:67]
	v_pk_fma_f32 v[20:21], v[52:53], v[194:195], v[20:21]
	v_pk_fma_f32 v[22:23], v[54:55], v[196:197], v[22:23]
	v_pk_fma_f32 v[16:17], v[56:57], v[194:195], v[16:17]
	v_pk_fma_f32 v[18:19], v[58:59], v[196:197], v[18:19]
	s_waitcnt vmcnt(29)
	v_lshlrev_b32_e32 v198, 16, v132
	v_and_b32_e32 v199, 0xffff0000, v132
	v_lshlrev_b32_e32 v200, 16, v133
	v_and_b32_e32 v201, 0xffff0000, v133
	v_pk_fma_f32 v[28:29], v[48:49], v[198:199], v[64:65]
	v_pk_fma_f32 v[30:31], v[50:51], v[200:201], v[66:67]
	v_pk_fma_f32 v[24:25], v[52:53], v[198:199], v[24:25]
	v_pk_fma_f32 v[26:27], v[54:55], v[200:201], v[26:27]
	v_pk_fma_f32 v[20:21], v[56:57], v[198:199], v[20:21]
	v_pk_fma_f32 v[22:23], v[58:59], v[200:201], v[22:23]
	v_pk_fma_f32 v[16:17], v[60:61], v[198:199], v[16:17]
	v_pk_fma_f32 v[18:19], v[62:63], v[200:201], v[18:19]
	s_waitcnt vmcnt(28)
	v_lshlrev_b32_e32 v194, 16, v130
	v_and_b32_e32 v195, 0xffff0000, v130
	v_lshlrev_b32_e32 v196, 16, v131
	v_and_b32_e32 v197, 0xffff0000, v131
	v_pk_fma_f32 v[32:33], v[48:49], v[194:195], v[64:65]
	v_pk_fma_f32 v[34:35], v[50:51], v[196:197], v[66:67]
	v_pk_fma_f32 v[28:29], v[52:53], v[194:195], v[28:29]
	v_pk_fma_f32 v[30:31], v[54:55], v[196:197], v[30:31]
	v_pk_fma_f32 v[24:25], v[56:57], v[194:195], v[24:25]
	v_pk_fma_f32 v[26:27], v[58:59], v[196:197], v[26:27]
	v_pk_fma_f32 v[20:21], v[60:61], v[194:195], v[20:21]
	v_pk_fma_f32 v[22:23], v[62:63], v[196:197], v[22:23]
	s_waitcnt vmcnt(27)
	v_lshlrev_b32_e32 v198, 16, v128
	v_and_b32_e32 v199, 0xffff0000, v128
	v_lshlrev_b32_e32 v200, 16, v129
	v_and_b32_e32 v201, 0xffff0000, v129
	v_pk_fma_f32 v[36:37], v[48:49], v[198:199], v[64:65]
	v_pk_fma_f32 v[38:39], v[50:51], v[200:201], v[66:67]
	v_pk_fma_f32 v[32:33], v[52:53], v[198:199], v[32:33]
	v_pk_fma_f32 v[34:35], v[54:55], v[200:201], v[34:35]
	v_pk_fma_f32 v[28:29], v[56:57], v[198:199], v[28:29]
	v_pk_fma_f32 v[30:31], v[58:59], v[200:201], v[30:31]
	v_pk_fma_f32 v[24:25], v[60:61], v[198:199], v[24:25]
	v_pk_fma_f32 v[26:27], v[62:63], v[200:201], v[26:27]
	s_waitcnt vmcnt(26)
	v_lshlrev_b32_e32 v194, 16, v126
	v_and_b32_e32 v195, 0xffff0000, v126
	v_lshlrev_b32_e32 v196, 16, v127
	v_and_b32_e32 v197, 0xffff0000, v127
	v_pk_fma_f32 v[40:41], v[48:49], v[194:195], v[64:65]
	v_pk_fma_f32 v[42:43], v[50:51], v[196:197], v[66:67]
	v_pk_fma_f32 v[36:37], v[52:53], v[194:195], v[36:37]
	v_pk_fma_f32 v[38:39], v[54:55], v[196:197], v[38:39]
	v_pk_fma_f32 v[32:33], v[56:57], v[194:195], v[32:33]
	v_pk_fma_f32 v[34:35], v[58:59], v[196:197], v[34:35]
	v_pk_fma_f32 v[28:29], v[60:61], v[194:195], v[28:29]
	v_pk_fma_f32 v[30:31], v[62:63], v[196:197], v[30:31]
	s_waitcnt vmcnt(25)
; __device__ __forceinline__ unsigned cvt_pk_bf16(float lo, float hi) { unsigned r; asm volatile("v_cvt_pk_bf16_f32 %0, %1, %2" : "=v"(r) : "v"(lo), "v"(hi)); return r; }
; #define LAS __attribute__((address_space(3)))
; __device__ __forceinline__ float bflo(unsigned u) { return __uint_as_float(u << 16); }
; __device__ __forceinline__ float bfhi(unsigned u) { return __uint_as_float(u & 0xffff0000u); }
; __device__ __forceinline__ float siluf_(float v) { return v * __builtin_amdgcn_rcpf(1.0f + __expf(-v)); }
; __device__ __forceinline__ void ssd_item(const Params& p, LAS unsigned char* lds, int bl, int head, int dry) {
;     ...
;                 for (int j = 0; j < 8; ++j) { const int i = seg * 8 + j;
;                     const u32x2 x0 = raw[i], x1 = raw[i + 1], x2 = raw[i + 2], x3 = raw[i + 3];
;                     float v0 = cbv[0] + cw0[0] * bflo(x0.x) + cw1[0] * bflo(x1.x) + cw2[0] * bflo(x2.x) + cw3[0] * bflo(x3.x);
;                     float v1 = cbv[1] + cw0[1] * bfhi(x0.x) + cw1[1] * bfhi(x1.x) + cw2[1] * bfhi(x2.x) + cw3[1] * bfhi(x3.x);
;                     float v2 = cbv[2] + cw0[2] * bflo(x0.y) + cw1[2] * bflo(x1.y) + cw2[2] * bflo(x2.y) + cw3[2] * bflo(x3.y);
;                     float v3 = cbv[3] + cw0[3] * bfhi(x0.y) + cw1[3] * bfhi(x1.y) + cw2[3] * bfhi(x2.y) + cw3[3] * bfhi(x3.y);
;                     val[j][0] = siluf_(v0); val[j][1] = siluf_(v1); val[j][2] = siluf_(v2); val[j][3] = siluf_(v3); }
;                 const int lb = rg * 32 + seg * 8;
;                 if (kind != 0) { LAS bf16_t* rm = (kind == 1 ? BMm : CM) + lb * SLD + n4;
; #pragma unroll
;                     for (int j = 0; j < 8; ++j) { u32x2 o; o.x = cvt_pk_bf16(val[j][0], val[j][1]); o.y = cvt_pk_bf16(val[j][2], val[j][3]); *(LAS u32x2*)(rm + j * SLD) = o; } }
	v_lshlrev_b32_e32 v198, 16, v124
	v_and_b32_e32 v199, 0xffff0000, v124
	v_lshlrev_b32_e32 v200, 16, v125
	v_and_b32_e32 v201, 0xffff0000, v125
	v_pk_fma_f32 v[44:45], v[48:49], v[198:199], v[64:65]
	v_pk_fma_f32 v[46:47], v[50:51], v[200:201], v[66:67]
	v_pk_fma_f32 v[40:41], v[52:53], v[198:199], v[40:41]
	v_pk_fma_f32 v[42:43], v[54:55], v[200:201], v[42:43]
	v_pk_fma_f32 v[36:37], v[56:57], v[198:199], v[36:37]
	v_pk_fma_f32 v[38:39], v[58:59], v[200:201], v[38:39]
	v_pk_fma_f32 v[32:33], v[60:61], v[198:199], v[32:33]
	v_pk_fma_f32 v[34:35], v[62:63], v[200:201], v[34:35]
	s_waitcnt vmcnt(24)
	v_lshlrev_b32_e32 v194, 16, v122
	v_and_b32_e32 v195, 0xffff0000, v122
	v_lshlrev_b32_e32 v196, 16, v123
	v_and_b32_e32 v197, 0xffff0000, v123
	v_pk_fma_f32 v[44:45], v[52:53], v[194:195], v[44:45]
	v_pk_fma_f32 v[46:47], v[54:55], v[196:197], v[46:47]
	v_pk_fma_f32 v[40:41], v[56:57], v[194:195], v[40:41]
	v_pk_fma_f32 v[42:43], v[58:59], v[196:197], v[42:43]
	v_pk_fma_f32 v[36:37], v[60:61], v[194:195], v[36:37]
	v_pk_fma_f32 v[38:39], v[62:63], v[196:197], v[38:39]
	s_waitcnt vmcnt(23)
	v_lshlrev_b32_e32 v198, 16, v120
	v_and_b32_e32 v199, 0xffff0000, v120
	v_lshlrev_b32_e32 v200, 16, v121
	v_and_b32_e32 v201, 0xffff0000, v121
	v_pk_fma_f32 v[44:45], v[56:57], v[198:199], v[44:45]
	v_pk_fma_f32 v[46:47], v[58:59], v[200:201], v[46:47]
	v_pk_fma_f32 v[40:41], v[60:61], v[198:199], v[40:41]
	v_pk_fma_f32 v[42:43], v[62:63], v[200:201], v[42:43]
	s_waitcnt vmcnt(22)
	v_lshlrev_b32_e32 v194, 16, v118
	v_and_b32_e32 v195, 0xffff0000, v118
	v_lshlrev_b32_e32 v196, 16, v119
	v_and_b32_e32 v197, 0xffff0000, v119
	v_pk_fma_f32 v[44:45], v[60:61], v[194:195], v[44:45]
	v_pk_fma_f32 v[46:47], v[62:63], v[196:197], v[46:47]
	v_pk_mul_f32 v[202:203], v[16:17], v[214:215]
	v_pk_mul_f32 v[204:205], v[18:19], v[214:215]
	v_exp_f32_e32 v202, v202
	v_exp_f32_e32 v203, v203
	v_exp_f32_e32 v204, v204
	v_exp_f32_e32 v205, v205
	v_pk_add_f32 v[202:203], v[202:203], v[216:217]
	v_pk_add_f32 v[204:205], v[204:205], v[216:217]
	v_rcp_f32_e32 v202, v202
	v_rcp_f32_e32 v203, v203
	v_rcp_f32_e32 v204, v204
	v_rcp_f32_e32 v205, v205
	v_pk_mul_f32 v[16:17], v[16:17], v[202:203]
	v_pk_mul_f32 v[18:19], v[18:19], v[204:205]
	v_pk_mul_f32 v[202:203], v[20:21], v[214:215]
	v_pk_mul_f32 v[204:205], v[22:23], v[214:215]
	v_exp_f32_e32 v202, v202
	v_exp_f32_e32 v203, v203
	v_exp_f32_e32 v204, v204
	v_exp_f32_e32 v205, v205
	v_pk_add_f32 v[202:203], v[202:203], v[216:217]
	v_pk_add_f32 v[204:205], v[204:205], v[216:217]
	v_rcp_f32_e32 v202, v202
	v_rcp_f32_e32 v203, v203
	v_rcp_f32_e32 v204, v204
	v_rcp_f32_e32 v205, v205
	v_pk_mul_f32 v[20:21], v[20:21], v[202:203]
	v_pk_mul_f32 v[22:23], v[22:23], v[204:205]
	v_pk_mul_f32 v[202:203], v[24:25], v[214:215]
	v_pk_mul_f32 v[204:205], v[26:27], v[214:215]
	v_exp_f32_e32 v202, v202
	v_exp_f32_e32 v203, v203
	v_exp_f32_e32 v204, v204
	v_exp_f32_e32 v205, v205
	v_pk_add_f32 v[202:203], v[202:203], v[216:217]
	v_pk_add_f32 v[204:205], v[204:205], v[216:217]
	v_rcp_f32_e32 v202, v202
	v_rcp_f32_e32 v203, v203
	v_rcp_f32_e32 v204, v204
	v_rcp_f32_e32 v205, v205
	v_pk_mul_f32 v[24:25], v[24:25], v[202:203]
	v_pk_mul_f32 v[26:27], v[26:27], v[204:205]
	v_pk_mul_f32 v[202:203], v[28:29], v[214:215]
	v_pk_mul_f32 v[204:205], v[30:31], v[214:215]
	v_exp_f32_e32 v202, v202
	v_exp_f32_e32 v203, v203
	v_exp_f32_e32 v204, v204
	v_exp_f32_e32 v205, v205
	v_pk_add_f32 v[202:203], v[202:203], v[216:217]
	v_pk_add_f32 v[204:205], v[204:205], v[216:217]
	v_rcp_f32_e32 v202, v202
	v_rcp_f32_e32 v203, v203
	v_rcp_f32_e32 v204, v204
	v_rcp_f32_e32 v205, v205
	v_pk_mul_f32 v[28:29], v[28:29], v[202:203]
	v_pk_mul_f32 v[30:31], v[30:31], v[204:205]
	v_pk_mul_f32 v[202:203], v[32:33], v[214:215]
	v_pk_mul_f32 v[204:205], v[34:35], v[214:215]
	v_exp_f32_e32 v202, v202
	v_exp_f32_e32 v203, v203
	v_exp_f32_e32 v204, v204
	v_exp_f32_e32 v205, v205
	v_pk_add_f32 v[202:203], v[202:203], v[216:217]
	v_pk_add_f32 v[204:205], v[204:205], v[216:217]
	v_rcp_f32_e32 v202, v202
	v_rcp_f32_e32 v203, v203
	v_rcp_f32_e32 v204, v204
	v_rcp_f32_e32 v205, v205
	v_pk_mul_f32 v[32:33], v[32:33], v[202:203]
	v_pk_mul_f32 v[34:35], v[34:35], v[204:205]
	v_pk_mul_f32 v[202:203], v[36:37], v[214:215]
	v_pk_mul_f32 v[204:205], v[38:39], v[214:215]
	v_exp_f32_e32 v202, v202
	v_exp_f32_e32 v203, v203
	v_exp_f32_e32 v204, v204
	v_exp_f32_e32 v205, v205
	v_pk_add_f32 v[202:203], v[202:203], v[216:217]
	v_pk_add_f32 v[204:205], v[204:205], v[216:217]
	v_rcp_f32_e32 v202, v202
	v_rcp_f32_e32 v203, v203
	v_rcp_f32_e32 v204, v204
	v_rcp_f32_e32 v205, v205
	v_pk_mul_f32 v[36:37], v[36:37], v[202:203]
	v_pk_mul_f32 v[38:39], v[38:39], v[204:205]
	v_pk_mul_f32 v[202:203], v[40:41], v[214:215]
	v_pk_mul_f32 v[204:205], v[42:43], v[214:215]
	v_exp_f32_e32 v202, v202
	v_exp_f32_e32 v203, v203
	v_exp_f32_e32 v204, v204
	v_exp_f32_e32 v205, v205
	v_pk_add_f32 v[202:203], v[202:203], v[216:217]
	v_pk_add_f32 v[204:205], v[204:205], v[216:217]
	v_rcp_f32_e32 v202, v202
	v_rcp_f32_e32 v203, v203
	v_rcp_f32_e32 v204, v204
	v_rcp_f32_e32 v205, v205
	v_pk_mul_f32 v[40:41], v[40:41], v[202:203]
	v_pk_mul_f32 v[42:43], v[42:43], v[204:205]
	v_pk_mul_f32 v[202:203], v[44:45], v[214:215]
	v_pk_mul_f32 v[204:205], v[46:47], v[214:215]
	v_exp_f32_e32 v202, v202
	v_exp_f32_e32 v203, v203
	v_exp_f32_e32 v204, v204
	v_exp_f32_e32 v205, v205
	v_pk_add_f32 v[202:203], v[202:203], v[216:217]
	v_pk_add_f32 v[204:205], v[204:205], v[216:217]
	v_rcp_f32_e32 v202, v202
	v_rcp_f32_e32 v203, v203
	v_rcp_f32_e32 v204, v204
	v_rcp_f32_e32 v205, v205
	v_pk_mul_f32 v[44:45], v[44:45], v[202:203]
	v_pk_mul_f32 v[46:47], v[46:47], v[204:205]
	s_and_saveexec_b64 vcc, s[38:39]
	s_cbranch_execz .Lcv_rm_1
	v_cvt_pk_bf16_f32 v194, v16, v17
	v_cvt_pk_bf16_f32 v195, v18, v19
	ds_write_b64 v187, v[194:195] offset:2176
	v_cvt_pk_bf16_f32 v196, v20, v21
	v_cvt_pk_bf16_f32 v197, v22, v23
	ds_write_b64 v187, v[196:197] offset:2448
	v_cvt_pk_bf16_f32 v194, v24, v25
	v_cvt_pk_bf16_f32 v195, v26, v27
	ds_write_b64 v187, v[194:195] offset:2720
	v_cvt_pk_bf16_f32 v196, v28, v29
	v_cvt_pk_bf16_f32 v197, v30, v31
	ds_write_b64 v187, v[196:197] offset:2992
	v_cvt_pk_bf16_f32 v194, v32, v33
	v_cvt_pk_bf16_f32 v195, v34, v35
	ds_write_b64 v187, v[194:195] offset:3264
	v_cvt_pk_bf16_f32 v196, v36, v37
	v_cvt_pk_bf16_f32 v197, v38, v39
	ds_write_b64 v187, v[196:197] offset:3536
	v_cvt_pk_bf16_f32 v194, v40, v41
	v_cvt_pk_bf16_f32 v195, v42, v43
	ds_write_b64 v187, v[194:195] offset:3808
	v_cvt_pk_bf16_f32 v196, v44, v45
	v_cvt_pk_bf16_f32 v197, v46, v47
	ds_write_b64 v187, v[196:197] offset:4080
; __device__ __forceinline__ unsigned cvt_pk_bf16(float lo, float hi) { unsigned r; asm volatile("v_cvt_pk_bf16_f32 %0, %1, %2" : "=v"(r) : "v"(lo), "v"(hi)); return r; }
; #define LAS __attribute__((address_space(3)))
; __device__ __forceinline__ float bflo(unsigned u) { return __uint_as_float(u << 16); }
; __device__ __forceinline__ float bfhi(unsigned u) { return __uint_as_float(u & 0xffff0000u); }
; __device__ __forceinline__ void ssd_item(const Params& p, LAS unsigned char* lds, int bl, int head, int dry) {
;     ...
;                 for (int j = 0; j < 8; ++j) { const int i = seg * 8 + j;
;                     const u32x2 x0 = raw[i], x1 = raw[i + 1], x2 = raw[i + 2], x3 = raw[i + 3];
;                     float v0 = cbv[0] + cw0[0] * bflo(x0.x) + cw1[0] * bflo(x1.x) + cw2[0] * bflo(x2.x) + cw3[0] * bflo(x3.x);
;                     float v1 = cbv[1] + cw0[1] * bfhi(x0.x) + cw1[1] * bfhi(x1.x) + cw2[1] * bfhi(x2.x) + cw3[1] * bfhi(x3.x);
;                     float v2 = cbv[2] + cw0[2] * bflo(x0.y) + cw1[2] * bflo(x1.y) + cw2[2] * bflo(x2.y) + cw3[2] * bflo(x3.y);
;                     float v3 = cbv[3] + cw0[3] * bfhi(x0.y) + cw1[3] * bfhi(x1.y) + cw2[3] * bfhi(x2.y) + cw3[3] * bfhi(x3.y);
;     ...
;                 if (kind != 2) { LAS float* sc = (kind == 0 ? fdt : fwl) + lb; LAS bf16_t* tp = (kind == 0 ? XT : BT) + n4 * SLD + lb;
;                     float scl[8];
; #pragma unroll
;                     for (int j = 0; j < 8; ++j) scl[j] = sc[j];
; #pragma unroll
;                     for (int e = 0; e < 4; ++e) { u32x4 o; o.x = cvt_pk_bf16(val[0][e] * scl[0], val[1][e] * scl[1]); o.y = cvt_pk_bf16(val[2][e] * scl[2], val[3][e] * scl[3]);
;                         o.z = cvt_pk_bf16(val[4][e] * scl[4], val[5][e] * scl[5]); o.w = cvt_pk_bf16(val[6][e] * scl[6], val[7][e] * scl[7]); *(LAS u32x4*)(tp + e * SLD) = o; } }
.Lcv_rm_1:
	s_or_b64 exec, exec, vcc
	s_and_saveexec_b64 vcc, s[34:35]
	s_cbranch_execz .Lcv_tr_1
	ds_read_b128 v[206:209], v218 offset:32
	ds_read_b128 v[210:213], v218 offset:48
	s_waitcnt lgkmcnt(0)
	v_pk_mul_f32 v[16:17], v[16:17], v[206:207] op_sel_hi:[1,0]
	v_pk_mul_f32 v[18:19], v[18:19], v[206:207] op_sel_hi:[1,0]
	v_pk_mul_f32 v[20:21], v[20:21], v[206:207] op_sel:[0,1] op_sel_hi:[1,1]
	v_pk_mul_f32 v[22:23], v[22:23], v[206:207] op_sel:[0,1] op_sel_hi:[1,1]
	v_pk_mul_f32 v[24:25], v[24:25], v[208:209] op_sel_hi:[1,0]
	v_pk_mul_f32 v[26:27], v[26:27], v[208:209] op_sel_hi:[1,0]
	v_pk_mul_f32 v[28:29], v[28:29], v[208:209] op_sel:[0,1] op_sel_hi:[1,1]
	v_pk_mul_f32 v[30:31], v[30:31], v[208:209] op_sel:[0,1] op_sel_hi:[1,1]
	v_pk_mul_f32 v[32:33], v[32:33], v[210:211] op_sel_hi:[1,0]
	v_pk_mul_f32 v[34:35], v[34:35], v[210:211] op_sel_hi:[1,0]
	v_pk_mul_f32 v[36:37], v[36:37], v[210:211] op_sel:[0,1] op_sel_hi:[1,1]
	v_pk_mul_f32 v[38:39], v[38:39], v[210:211] op_sel:[0,1] op_sel_hi:[1,1]
	v_pk_mul_f32 v[40:41], v[40:41], v[212:213] op_sel_hi:[1,0]
	v_pk_mul_f32 v[42:43], v[42:43], v[212:213] op_sel_hi:[1,0]
	v_pk_mul_f32 v[44:45], v[44:45], v[212:213] op_sel:[0,1] op_sel_hi:[1,1]
	v_pk_mul_f32 v[46:47], v[46:47], v[212:213] op_sel:[0,1] op_sel_hi:[1,1]
	v_cvt_pk_bf16_f32 v236, v16, v20
	v_cvt_pk_bf16_f32 v237, v24, v28
	v_cvt_pk_bf16_f32 v238, v32, v36
	v_cvt_pk_bf16_f32 v239, v40, v44
	ds_write_b128 v178, v[236:239] offset:16
	v_cvt_pk_bf16_f32 v198, v17, v21
	v_cvt_pk_bf16_f32 v199, v25, v29
	v_cvt_pk_bf16_f32 v200, v33, v37
	v_cvt_pk_bf16_f32 v201, v41, v45
	ds_write_b128 v178, v[198:201] offset:288
	v_cvt_pk_bf16_f32 v236, v18, v22
	v_cvt_pk_bf16_f32 v237, v26, v30
	v_cvt_pk_bf16_f32 v238, v34, v38
	v_cvt_pk_bf16_f32 v239, v42, v46
	ds_write_b128 v178, v[236:239] offset:560
	v_cvt_pk_bf16_f32 v198, v19, v23
	v_cvt_pk_bf16_f32 v199, v27, v31
	v_cvt_pk_bf16_f32 v200, v35, v39
	v_cvt_pk_bf16_f32 v201, v43, v47
	ds_write_b128 v178, v[198:201] offset:832
.Lcv_tr_1:
	s_or_b64 exec, exec, vcc
	v_lshlrev_b32_e32 v194, 16, v122
	v_and_b32_e32 v195, 0xffff0000, v122
	v_lshlrev_b32_e32 v196, 16, v123
	v_and_b32_e32 v197, 0xffff0000, v123
	v_pk_fma_f32 v[16:17], v[48:49], v[194:195], v[64:65]
	v_pk_fma_f32 v[18:19], v[50:51], v[196:197], v[66:67]
	v_lshlrev_b32_e32 v198, 16, v120
	v_and_b32_e32 v199, 0xffff0000, v120
	v_lshlrev_b32_e32 v200, 16, v121
	v_and_b32_e32 v201, 0xffff0000, v121
	v_pk_fma_f32 v[20:21], v[48:49], v[198:199], v[64:65]
	v_pk_fma_f32 v[22:23], v[50:51], v[200:201], v[66:67]
	v_pk_fma_f32 v[16:17], v[52:53], v[198:199], v[16:17]
	v_pk_fma_f32 v[18:19], v[54:55], v[200:201], v[18:19]
	v_lshlrev_b32_e32 v194, 16, v118
	v_and_b32_e32 v195, 0xffff0000, v118
	v_lshlrev_b32_e32 v196, 16, v119
	v_and_b32_e32 v197, 0xffff0000, v119
	v_pk_fma_f32 v[24:25], v[48:49], v[194:195], v[64:65]
	v_pk_fma_f32 v[26:27], v[50:51], v[196:197], v[66:67]
	v_pk_fma_f32 v[20:21], v[52:53], v[194:195], v[20:21]
	v_pk_fma_f32 v[22:23], v[54:55], v[196:197], v[22:23]
	v_pk_fma_f32 v[16:17], v[56:57], v[194:195], v[16:17]
	v_pk_fma_f32 v[18:19], v[58:59], v[196:197], v[18:19]
	s_waitcnt vmcnt(21)
	v_lshlrev_b32_e32 v198, 16, v116
	v_and_b32_e32 v199, 0xffff0000, v116
	v_lshlrev_b32_e32 v200, 16, v117
	v_and_b32_e32 v201, 0xffff0000, v117
	v_pk_fma_f32 v[28:29], v[48:49], v[198:199], v[64:65]
	v_pk_fma_f32 v[30:31], v[50:51], v[200:201], v[66:67]
	v_pk_fma_f32 v[24:25], v[52:53], v[198:199], v[24:25]
	v_pk_fma_f32 v[26:27], v[54:55], v[200:201], v[26:27]
	v_pk_fma_f32 v[20:21], v[56:57], v[198:199], v[20:21]
	v_pk_fma_f32 v[22:23], v[58:59], v[200:201], v[22:23]
	v_pk_fma_f32 v[16:17], v[60:61], v[198:199], v[16:17]
	v_pk_fma_f32 v[18:19], v[62:63], v[200:201], v[18:19]
	s_waitcnt vmcnt(20)
	v_lshlrev_b32_e32 v194, 16, v114
	v_and_b32_e32 v195, 0xffff0000, v114
	v_lshlrev_b32_e32 v196, 16, v115
	v_and_b32_e32 v197, 0xffff0000, v115
	v_pk_fma_f32 v[32:33], v[48:49], v[194:195], v[64:65]
	v_pk_fma_f32 v[34:35], v[50:51], v[196:197], v[66:67]
	v_pk_fma_f32 v[28:29], v[52:53], v[194:195], v[28:29]
	v_pk_fma_f32 v[30:31], v[54:55], v[196:197], v[30:31]
	v_pk_fma_f32 v[24:25], v[56:57], v[194:195], v[24:25]
	v_pk_fma_f32 v[26:27], v[58:59], v[196:197], v[26:27]
	v_pk_fma_f32 v[20:21], v[60:61], v[194:195], v[20:21]
	v_pk_fma_f32 v[22:23], v[62:63], v[196:197], v[22:23]
	s_waitcnt vmcnt(19)
	v_lshlrev_b32_e32 v198, 16, v112
	v_and_b32_e32 v199, 0xffff0000, v112
	v_lshlrev_b32_e32 v200, 16, v113
	v_and_b32_e32 v201, 0xffff0000, v113
	v_pk_fma_f32 v[36:37], v[48:49], v[198:199], v[64:65]
	v_pk_fma_f32 v[38:39], v[50:51], v[200:201], v[66:67]
	v_pk_fma_f32 v[32:33], v[52:53], v[198:199], v[32:33]
	v_pk_fma_f32 v[34:35], v[54:55], v[200:201], v[34:35]
	v_pk_fma_f32 v[28:29], v[56:57], v[198:199], v[28:29]
	v_pk_fma_f32 v[30:31], v[58:59], v[200:201], v[30:31]
	v_pk_fma_f32 v[24:25], v[60:61], v[198:199], v[24:25]
	v_pk_fma_f32 v[26:27], v[62:63], v[200:201], v[26:27]
	s_waitcnt vmcnt(18)
	v_lshlrev_b32_e32 v194, 16, v110
	v_and_b32_e32 v195, 0xffff0000, v110
	v_lshlrev_b32_e32 v196, 16, v111
	v_and_b32_e32 v197, 0xffff0000, v111
	v_pk_fma_f32 v[40:41], v[48:49], v[194:195], v[64:65]
	v_pk_fma_f32 v[42:43], v[50:51], v[196:197], v[66:67]
	v_pk_fma_f32 v[36:37], v[52:53], v[194:195], v[36:37]
	v_pk_fma_f32 v[38:39], v[54:55], v[196:197], v[38:39]
	v_pk_fma_f32 v[32:33], v[56:57], v[194:195], v[32:33]
	v_pk_fma_f32 v[34:35], v[58:59], v[196:197], v[34:35]
	v_pk_fma_f32 v[28:29], v[60:61], v[194:195], v[28:29]
	v_pk_fma_f32 v[30:31], v[62:63], v[196:197], v[30:31]
	s_waitcnt vmcnt(17)
; __device__ __forceinline__ unsigned cvt_pk_bf16(float lo, float hi) { unsigned r; asm volatile("v_cvt_pk_bf16_f32 %0, %1, %2" : "=v"(r) : "v"(lo), "v"(hi)); return r; }
; #define LAS __attribute__((address_space(3)))
; __device__ __forceinline__ float bflo(unsigned u) { return __uint_as_float(u << 16); }
; __device__ __forceinline__ float bfhi(unsigned u) { return __uint_as_float(u & 0xffff0000u); }
; __device__ __forceinline__ float siluf_(float v) { return v * __builtin_amdgcn_rcpf(1.0f + __expf(-v)); }
; __device__ __forceinline__ void ssd_item(const Params& p, LAS unsigned char* lds, int bl, int head, int dry) {
;     ...
;                 for (int j = 0; j < 8; ++j) { const int i = seg * 8 + j;
;                     const u32x2 x0 = raw[i], x1 = raw[i + 1], x2 = raw[i + 2], x3 = raw[i + 3];
;                     float v0 = cbv[0] + cw0[0] * bflo(x0.x) + cw1[0] * bflo(x1.x) + cw2[0] * bflo(x2.x) + cw3[0] * bflo(x3.x);
;                     float v1 = cbv[1] + cw0[1] * bfhi(x0.x) + cw1[1] * bfhi(x1.x) + cw2[1] * bfhi(x2.x) + cw3[1] * bfhi(x3.x);
;                     float v2 = cbv[2] + cw0[2] * bflo(x0.y) + cw1[2] * bflo(x1.y) + cw2[2] * bflo(x2.y) + cw3[2] * bflo(x3.y);
;                     float v3 = cbv[3] + cw0[3] * bfhi(x0.y) + cw1[3] * bfhi(x1.y) + cw2[3] * bfhi(x2.y) + cw3[3] * bfhi(x3.y);
;                     val[j][0] = siluf_(v0); val[j][1] = siluf_(v1); val[j][2] = siluf_(v2); val[j][3] = siluf_(v3); }
;                 const int lb = rg * 32 + seg * 8;
;                 if (kind != 0) { LAS bf16_t* rm = (kind == 1 ? BMm : CM) + lb * SLD + n4;
; #pragma unroll
;                     for (int j = 0; j < 8; ++j) { u32x2 o; o.x = cvt_pk_bf16(val[j][0], val[j][1]); o.y = cvt_pk_bf16(val[j][2], val[j][3]); *(LAS u32x2*)(rm + j * SLD) = o; } }
	v_lshlrev_b32_e32 v198, 16, v108
	v_and_b32_e32 v199, 0xffff0000, v108
	v_lshlrev_b32_e32 v200, 16, v109
	v_and_b32_e32 v201, 0xffff0000, v109
	v_pk_fma_f32 v[44:45], v[48:49], v[198:199], v[64:65]
	v_pk_fma_f32 v[46:47], v[50:51], v[200:201], v[66:67]
	v_pk_fma_f32 v[40:41], v[52:53], v[198:199], v[40:41]
	v_pk_fma_f32 v[42:43], v[54:55], v[200:201], v[42:43]
	v_pk_fma_f32 v[36:37], v[56:57], v[198:199], v[36:37]
	v_pk_fma_f32 v[38:39], v[58:59], v[200:201], v[38:39]
	v_pk_fma_f32 v[32:33], v[60:61], v[198:199], v[32:33]
	v_pk_fma_f32 v[34:35], v[62:63], v[200:201], v[34:35]
	s_waitcnt vmcnt(16)
	v_lshlrev_b32_e32 v194, 16, v106
	v_and_b32_e32 v195, 0xffff0000, v106
	v_lshlrev_b32_e32 v196, 16, v107
	v_and_b32_e32 v197, 0xffff0000, v107
	v_pk_fma_f32 v[44:45], v[52:53], v[194:195], v[44:45]
	v_pk_fma_f32 v[46:47], v[54:55], v[196:197], v[46:47]
	v_pk_fma_f32 v[40:41], v[56:57], v[194:195], v[40:41]
	v_pk_fma_f32 v[42:43], v[58:59], v[196:197], v[42:43]
	v_pk_fma_f32 v[36:37], v[60:61], v[194:195], v[36:37]
	v_pk_fma_f32 v[38:39], v[62:63], v[196:197], v[38:39]
	s_waitcnt vmcnt(15)
	v_lshlrev_b32_e32 v198, 16, v102
	v_and_b32_e32 v199, 0xffff0000, v102
	v_lshlrev_b32_e32 v200, 16, v103
	v_and_b32_e32 v201, 0xffff0000, v103
	v_pk_fma_f32 v[44:45], v[56:57], v[198:199], v[44:45]
	v_pk_fma_f32 v[46:47], v[58:59], v[200:201], v[46:47]
	v_pk_fma_f32 v[40:41], v[60:61], v[198:199], v[40:41]
	v_pk_fma_f32 v[42:43], v[62:63], v[200:201], v[42:43]
	s_waitcnt vmcnt(14)
	v_lshlrev_b32_e32 v194, 16, v100
	v_and_b32_e32 v195, 0xffff0000, v100
	v_lshlrev_b32_e32 v196, 16, v101
	v_and_b32_e32 v197, 0xffff0000, v101
	v_pk_fma_f32 v[44:45], v[60:61], v[194:195], v[44:45]
	v_pk_fma_f32 v[46:47], v[62:63], v[196:197], v[46:47]
	v_pk_mul_f32 v[202:203], v[16:17], v[214:215]
	v_pk_mul_f32 v[204:205], v[18:19], v[214:215]
	v_exp_f32_e32 v202, v202
	v_exp_f32_e32 v203, v203
	v_exp_f32_e32 v204, v204
	v_exp_f32_e32 v205, v205
	v_pk_add_f32 v[202:203], v[202:203], v[216:217]
	v_pk_add_f32 v[204:205], v[204:205], v[216:217]
	v_rcp_f32_e32 v202, v202
	v_rcp_f32_e32 v203, v203
	v_rcp_f32_e32 v204, v204
	v_rcp_f32_e32 v205, v205
	v_pk_mul_f32 v[16:17], v[16:17], v[202:203]
	v_pk_mul_f32 v[18:19], v[18:19], v[204:205]
	v_pk_mul_f32 v[202:203], v[20:21], v[214:215]
	v_pk_mul_f32 v[204:205], v[22:23], v[214:215]
	v_exp_f32_e32 v202, v202
	v_exp_f32_e32 v203, v203
	v_exp_f32_e32 v204, v204
	v_exp_f32_e32 v205, v205
	v_pk_add_f32 v[202:203], v[202:203], v[216:217]
	v_pk_add_f32 v[204:205], v[204:205], v[216:217]
	v_rcp_f32_e32 v202, v202
	v_rcp_f32_e32 v203, v203
	v_rcp_f32_e32 v204, v204
	v_rcp_f32_e32 v205, v205
	v_pk_mul_f32 v[20:21], v[20:21], v[202:203]
	v_pk_mul_f32 v[22:23], v[22:23], v[204:205]
	v_pk_mul_f32 v[202:203], v[24:25], v[214:215]
	v_pk_mul_f32 v[204:205], v[26:27], v[214:215]
	v_exp_f32_e32 v202, v202
	v_exp_f32_e32 v203, v203
	v_exp_f32_e32 v204, v204
	v_exp_f32_e32 v205, v205
	v_pk_add_f32 v[202:203], v[202:203], v[216:217]
	v_pk_add_f32 v[204:205], v[204:205], v[216:217]
	v_rcp_f32_e32 v202, v202
	v_rcp_f32_e32 v203, v203
	v_rcp_f32_e32 v204, v204
	v_rcp_f32_e32 v205, v205
	v_pk_mul_f32 v[24:25], v[24:25], v[202:203]
	v_pk_mul_f32 v[26:27], v[26:27], v[204:205]
	v_pk_mul_f32 v[202:203], v[28:29], v[214:215]
	v_pk_mul_f32 v[204:205], v[30:31], v[214:215]
	v_exp_f32_e32 v202, v202
	v_exp_f32_e32 v203, v203
	v_exp_f32_e32 v204, v204
	v_exp_f32_e32 v205, v205
	v_pk_add_f32 v[202:203], v[202:203], v[216:217]
	v_pk_add_f32 v[204:205], v[204:205], v[216:217]
	v_rcp_f32_e32 v202, v202
	v_rcp_f32_e32 v203, v203
	v_rcp_f32_e32 v204, v204
	v_rcp_f32_e32 v205, v205
	v_pk_mul_f32 v[28:29], v[28:29], v[202:203]
	v_pk_mul_f32 v[30:31], v[30:31], v[204:205]
	v_pk_mul_f32 v[202:203], v[32:33], v[214:215]
	v_pk_mul_f32 v[204:205], v[34:35], v[214:215]
	v_exp_f32_e32 v202, v202
	v_exp_f32_e32 v203, v203
	v_exp_f32_e32 v204, v204
	v_exp_f32_e32 v205, v205
	v_pk_add_f32 v[202:203], v[202:203], v[216:217]
	v_pk_add_f32 v[204:205], v[204:205], v[216:217]
	v_rcp_f32_e32 v202, v202
	v_rcp_f32_e32 v203, v203
	v_rcp_f32_e32 v204, v204
	v_rcp_f32_e32 v205, v205
	v_pk_mul_f32 v[32:33], v[32:33], v[202:203]
	v_pk_mul_f32 v[34:35], v[34:35], v[204:205]
	v_pk_mul_f32 v[202:203], v[36:37], v[214:215]
	v_pk_mul_f32 v[204:205], v[38:39], v[214:215]
	v_exp_f32_e32 v202, v202
	v_exp_f32_e32 v203, v203
	v_exp_f32_e32 v204, v204
	v_exp_f32_e32 v205, v205
	v_pk_add_f32 v[202:203], v[202:203], v[216:217]
	v_pk_add_f32 v[204:205], v[204:205], v[216:217]
	v_rcp_f32_e32 v202, v202
	v_rcp_f32_e32 v203, v203
	v_rcp_f32_e32 v204, v204
	v_rcp_f32_e32 v205, v205
	v_pk_mul_f32 v[36:37], v[36:37], v[202:203]
	v_pk_mul_f32 v[38:39], v[38:39], v[204:205]
	v_pk_mul_f32 v[202:203], v[40:41], v[214:215]
	v_pk_mul_f32 v[204:205], v[42:43], v[214:215]
	v_exp_f32_e32 v202, v202
	v_exp_f32_e32 v203, v203
	v_exp_f32_e32 v204, v204
	v_exp_f32_e32 v205, v205
	v_pk_add_f32 v[202:203], v[202:203], v[216:217]
	v_pk_add_f32 v[204:205], v[204:205], v[216:217]
	v_rcp_f32_e32 v202, v202
	v_rcp_f32_e32 v203, v203
	v_rcp_f32_e32 v204, v204
	v_rcp_f32_e32 v205, v205
	v_pk_mul_f32 v[40:41], v[40:41], v[202:203]
	v_pk_mul_f32 v[42:43], v[42:43], v[204:205]
	v_pk_mul_f32 v[202:203], v[44:45], v[214:215]
	v_pk_mul_f32 v[204:205], v[46:47], v[214:215]
	v_exp_f32_e32 v202, v202
	v_exp_f32_e32 v203, v203
	v_exp_f32_e32 v204, v204
	v_exp_f32_e32 v205, v205
	v_pk_add_f32 v[202:203], v[202:203], v[216:217]
	v_pk_add_f32 v[204:205], v[204:205], v[216:217]
	v_rcp_f32_e32 v202, v202
	v_rcp_f32_e32 v203, v203
	v_rcp_f32_e32 v204, v204
	v_rcp_f32_e32 v205, v205
	v_pk_mul_f32 v[44:45], v[44:45], v[202:203]
	v_pk_mul_f32 v[46:47], v[46:47], v[204:205]
	s_and_saveexec_b64 vcc, s[38:39]
	s_cbranch_execz .Lcv_rm_2
	v_cvt_pk_bf16_f32 v194, v16, v17
	v_cvt_pk_bf16_f32 v195, v18, v19
	ds_write_b64 v187, v[194:195] offset:4352
	v_cvt_pk_bf16_f32 v196, v20, v21
	v_cvt_pk_bf16_f32 v197, v22, v23
	ds_write_b64 v187, v[196:197] offset:4624
	v_cvt_pk_bf16_f32 v194, v24, v25
	v_cvt_pk_bf16_f32 v195, v26, v27
	ds_write_b64 v187, v[194:195] offset:4896
	v_cvt_pk_bf16_f32 v196, v28, v29
	v_cvt_pk_bf16_f32 v197, v30, v31
	ds_write_b64 v187, v[196:197] offset:5168
	v_cvt_pk_bf16_f32 v194, v32, v33
	v_cvt_pk_bf16_f32 v195, v34, v35
	ds_write_b64 v187, v[194:195] offset:5440
	v_cvt_pk_bf16_f32 v196, v36, v37
	v_cvt_pk_bf16_f32 v197, v38, v39
	ds_write_b64 v187, v[196:197] offset:5712
	v_cvt_pk_bf16_f32 v194, v40, v41
	v_cvt_pk_bf16_f32 v195, v42, v43
	ds_write_b64 v187, v[194:195] offset:5984
	v_cvt_pk_bf16_f32 v196, v44, v45
	v_cvt_pk_bf16_f32 v197, v46, v47
	ds_write_b64 v187, v[196:197] offset:6256
; __device__ __forceinline__ unsigned cvt_pk_bf16(float lo, float hi) { unsigned r; asm volatile("v_cvt_pk_bf16_f32 %0, %1, %2" : "=v"(r) : "v"(lo), "v"(hi)); return r; }
; #define LAS __attribute__((address_space(3)))
; __device__ __forceinline__ float bflo(unsigned u) { return __uint_as_float(u << 16); }
; __device__ __forceinline__ float bfhi(unsigned u) { return __uint_as_float(u & 0xffff0000u); }
; __device__ __forceinline__ void ssd_item(const Params& p, LAS unsigned char* lds, int bl, int head, int dry) {
;     ...
;                 for (int j = 0; j < 8; ++j) { const int i = seg * 8 + j;
;                     const u32x2 x0 = raw[i], x1 = raw[i + 1], x2 = raw[i + 2], x3 = raw[i + 3];
;                     float v0 = cbv[0] + cw0[0] * bflo(x0.x) + cw1[0] * bflo(x1.x) + cw2[0] * bflo(x2.x) + cw3[0] * bflo(x3.x);
;                     float v1 = cbv[1] + cw0[1] * bfhi(x0.x) + cw1[1] * bfhi(x1.x) + cw2[1] * bfhi(x2.x) + cw3[1] * bfhi(x3.x);
;                     float v2 = cbv[2] + cw0[2] * bflo(x0.y) + cw1[2] * bflo(x1.y) + cw2[2] * bflo(x2.y) + cw3[2] * bflo(x3.y);
;                     float v3 = cbv[3] + cw0[3] * bfhi(x0.y) + cw1[3] * bfhi(x1.y) + cw2[3] * bfhi(x2.y) + cw3[3] * bfhi(x3.y);
;     ...
;                 if (kind != 2) { LAS float* sc = (kind == 0 ? fdt : fwl) + lb; LAS bf16_t* tp = (kind == 0 ? XT : BT) + n4 * SLD + lb;
;                     float scl[8];
; #pragma unroll
;                     for (int j = 0; j < 8; ++j) scl[j] = sc[j];
; #pragma unroll
;                     for (int e = 0; e < 4; ++e) { u32x4 o; o.x = cvt_pk_bf16(val[0][e] * scl[0], val[1][e] * scl[1]); o.y = cvt_pk_bf16(val[2][e] * scl[2], val[3][e] * scl[3]);
;                         o.z = cvt_pk_bf16(val[4][e] * scl[4], val[5][e] * scl[5]); o.w = cvt_pk_bf16(val[6][e] * scl[6], val[7][e] * scl[7]); *(LAS u32x4*)(tp + e * SLD) = o; } }
.Lcv_rm_2:
	s_or_b64 exec, exec, vcc
	s_and_saveexec_b64 vcc, s[34:35]
	s_cbranch_execz .Lcv_tr_2
	ds_read_b128 v[206:209], v218 offset:64
	ds_read_b128 v[210:213], v218 offset:80
	s_waitcnt lgkmcnt(0)
	v_pk_mul_f32 v[16:17], v[16:17], v[206:207] op_sel_hi:[1,0]
	v_pk_mul_f32 v[18:19], v[18:19], v[206:207] op_sel_hi:[1,0]
	v_pk_mul_f32 v[20:21], v[20:21], v[206:207] op_sel:[0,1] op_sel_hi:[1,1]
	v_pk_mul_f32 v[22:23], v[22:23], v[206:207] op_sel:[0,1] op_sel_hi:[1,1]
	v_pk_mul_f32 v[24:25], v[24:25], v[208:209] op_sel_hi:[1,0]
	v_pk_mul_f32 v[26:27], v[26:27], v[208:209] op_sel_hi:[1,0]
	v_pk_mul_f32 v[28:29], v[28:29], v[208:209] op_sel:[0,1] op_sel_hi:[1,1]
	v_pk_mul_f32 v[30:31], v[30:31], v[208:209] op_sel:[0,1] op_sel_hi:[1,1]
	v_pk_mul_f32 v[32:33], v[32:33], v[210:211] op_sel_hi:[1,0]
	v_pk_mul_f32 v[34:35], v[34:35], v[210:211] op_sel_hi:[1,0]
	v_pk_mul_f32 v[36:37], v[36:37], v[210:211] op_sel:[0,1] op_sel_hi:[1,1]
	v_pk_mul_f32 v[38:39], v[38:39], v[210:211] op_sel:[0,1] op_sel_hi:[1,1]
	v_pk_mul_f32 v[40:41], v[40:41], v[212:213] op_sel_hi:[1,0]
	v_pk_mul_f32 v[42:43], v[42:43], v[212:213] op_sel_hi:[1,0]
	v_pk_mul_f32 v[44:45], v[44:45], v[212:213] op_sel:[0,1] op_sel_hi:[1,1]
	v_pk_mul_f32 v[46:47], v[46:47], v[212:213] op_sel:[0,1] op_sel_hi:[1,1]
	v_cvt_pk_bf16_f32 v236, v16, v20
	v_cvt_pk_bf16_f32 v237, v24, v28
	v_cvt_pk_bf16_f32 v238, v32, v36
	v_cvt_pk_bf16_f32 v239, v40, v44
	ds_write_b128 v178, v[236:239] offset:32
	v_cvt_pk_bf16_f32 v198, v17, v21
	v_cvt_pk_bf16_f32 v199, v25, v29
	v_cvt_pk_bf16_f32 v200, v33, v37
	v_cvt_pk_bf16_f32 v201, v41, v45
	ds_write_b128 v178, v[198:201] offset:304
	v_cvt_pk_bf16_f32 v236, v18, v22
	v_cvt_pk_bf16_f32 v237, v26, v30
	v_cvt_pk_bf16_f32 v238, v34, v38
	v_cvt_pk_bf16_f32 v239, v42, v46
	ds_write_b128 v178, v[236:239] offset:576
	v_cvt_pk_bf16_f32 v198, v19, v23
	v_cvt_pk_bf16_f32 v199, v27, v31
	v_cvt_pk_bf16_f32 v200, v35, v39
	v_cvt_pk_bf16_f32 v201, v43, v47
	ds_write_b128 v178, v[198:201] offset:848
.Lcv_tr_2:
	s_or_b64 exec, exec, vcc
	v_lshlrev_b32_e32 v194, 16, v106
	v_and_b32_e32 v195, 0xffff0000, v106
	v_lshlrev_b32_e32 v196, 16, v107
	v_and_b32_e32 v197, 0xffff0000, v107
	v_pk_fma_f32 v[16:17], v[48:49], v[194:195], v[64:65]
	v_pk_fma_f32 v[18:19], v[50:51], v[196:197], v[66:67]
	v_lshlrev_b32_e32 v198, 16, v102
	v_and_b32_e32 v199, 0xffff0000, v102
	v_lshlrev_b32_e32 v200, 16, v103
	v_and_b32_e32 v201, 0xffff0000, v103
	v_pk_fma_f32 v[20:21], v[48:49], v[198:199], v[64:65]
	v_pk_fma_f32 v[22:23], v[50:51], v[200:201], v[66:67]
	v_pk_fma_f32 v[16:17], v[52:53], v[198:199], v[16:17]
	v_pk_fma_f32 v[18:19], v[54:55], v[200:201], v[18:19]
	v_lshlrev_b32_e32 v194, 16, v100
	v_and_b32_e32 v195, 0xffff0000, v100
	v_lshlrev_b32_e32 v196, 16, v101
	v_and_b32_e32 v197, 0xffff0000, v101
	v_pk_fma_f32 v[24:25], v[48:49], v[194:195], v[64:65]
	v_pk_fma_f32 v[26:27], v[50:51], v[196:197], v[66:67]
	v_pk_fma_f32 v[20:21], v[52:53], v[194:195], v[20:21]
	v_pk_fma_f32 v[22:23], v[54:55], v[196:197], v[22:23]
	v_pk_fma_f32 v[16:17], v[56:57], v[194:195], v[16:17]
	v_pk_fma_f32 v[18:19], v[58:59], v[196:197], v[18:19]
	s_waitcnt vmcnt(13)
	v_lshlrev_b32_e32 v198, 16, v94
	v_and_b32_e32 v199, 0xffff0000, v94
	v_lshlrev_b32_e32 v200, 16, v95
	v_and_b32_e32 v201, 0xffff0000, v95
	v_pk_fma_f32 v[28:29], v[48:49], v[198:199], v[64:65]
	v_pk_fma_f32 v[30:31], v[50:51], v[200:201], v[66:67]
	v_pk_fma_f32 v[24:25], v[52:53], v[198:199], v[24:25]
	v_pk_fma_f32 v[26:27], v[54:55], v[200:201], v[26:27]
	v_pk_fma_f32 v[20:21], v[56:57], v[198:199], v[20:21]
	v_pk_fma_f32 v[22:23], v[58:59], v[200:201], v[22:23]
	v_pk_fma_f32 v[16:17], v[60:61], v[198:199], v[16:17]
	v_pk_fma_f32 v[18:19], v[62:63], v[200:201], v[18:19]
	s_waitcnt vmcnt(12)
	v_lshlrev_b32_e32 v194, 16, v92
	v_and_b32_e32 v195, 0xffff0000, v92
	v_lshlrev_b32_e32 v196, 16, v93
	v_and_b32_e32 v197, 0xffff0000, v93
	v_pk_fma_f32 v[32:33], v[48:49], v[194:195], v[64:65]
	v_pk_fma_f32 v[34:35], v[50:51], v[196:197], v[66:67]
	v_pk_fma_f32 v[28:29], v[52:53], v[194:195], v[28:29]
	v_pk_fma_f32 v[30:31], v[54:55], v[196:197], v[30:31]
	v_pk_fma_f32 v[24:25], v[56:57], v[194:195], v[24:25]
	v_pk_fma_f32 v[26:27], v[58:59], v[196:197], v[26:27]
	v_pk_fma_f32 v[20:21], v[60:61], v[194:195], v[20:21]
	v_pk_fma_f32 v[22:23], v[62:63], v[196:197], v[22:23]
	s_waitcnt vmcnt(11)
	v_lshlrev_b32_e32 v198, 16, v88
	v_and_b32_e32 v199, 0xffff0000, v88
	v_lshlrev_b32_e32 v200, 16, v89
	v_and_b32_e32 v201, 0xffff0000, v89
	v_pk_fma_f32 v[36:37], v[48:49], v[198:199], v[64:65]
	v_pk_fma_f32 v[38:39], v[50:51], v[200:201], v[66:67]
	v_pk_fma_f32 v[32:33], v[52:53], v[198:199], v[32:33]
	v_pk_fma_f32 v[34:35], v[54:55], v[200:201], v[34:35]
	v_pk_fma_f32 v[28:29], v[56:57], v[198:199], v[28:29]
	v_pk_fma_f32 v[30:31], v[58:59], v[200:201], v[30:31]
	v_pk_fma_f32 v[24:25], v[60:61], v[198:199], v[24:25]
	v_pk_fma_f32 v[26:27], v[62:63], v[200:201], v[26:27]
	s_waitcnt vmcnt(10)
	v_lshlrev_b32_e32 v194, 16, v86
	v_and_b32_e32 v195, 0xffff0000, v86
	v_lshlrev_b32_e32 v196, 16, v87
	v_and_b32_e32 v197, 0xffff0000, v87
	v_pk_fma_f32 v[40:41], v[48:49], v[194:195], v[64:65]
	v_pk_fma_f32 v[42:43], v[50:51], v[196:197], v[66:67]
	v_pk_fma_f32 v[36:37], v[52:53], v[194:195], v[36:37]
	v_pk_fma_f32 v[38:39], v[54:55], v[196:197], v[38:39]
	v_pk_fma_f32 v[32:33], v[56:57], v[194:195], v[32:33]
	v_pk_fma_f32 v[34:35], v[58:59], v[196:197], v[34:35]
	v_pk_fma_f32 v[28:29], v[60:61], v[194:195], v[28:29]
	v_pk_fma_f32 v[30:31], v[62:63], v[196:197], v[30:31]
	s_waitcnt vmcnt(9)
; __device__ __forceinline__ unsigned cvt_pk_bf16(float lo, float hi) { unsigned r; asm volatile("v_cvt_pk_bf16_f32 %0, %1, %2" : "=v"(r) : "v"(lo), "v"(hi)); return r; }
; #define LAS __attribute__((address_space(3)))
; __device__ __forceinline__ float bflo(unsigned u) { return __uint_as_float(u << 16); }
; __device__ __forceinline__ float bfhi(unsigned u) { return __uint_as_float(u & 0xffff0000u); }
; __device__ __forceinline__ float siluf_(float v) { return v * __builtin_amdgcn_rcpf(1.0f + __expf(-v)); }
; __device__ __forceinline__ void ssd_item(const Params& p, LAS unsigned char* lds, int bl, int head, int dry) {
;     ...
;                 for (int j = 0; j < 8; ++j) { const int i = seg * 8 + j;
;                     const u32x2 x0 = raw[i], x1 = raw[i + 1], x2 = raw[i + 2], x3 = raw[i + 3];
;                     float v0 = cbv[0] + cw0[0] * bflo(x0.x) + cw1[0] * bflo(x1.x) + cw2[0] * bflo(x2.x) + cw3[0] * bflo(x3.x);
;                     float v1 = cbv[1] + cw0[1] * bfhi(x0.x) + cw1[1] * bfhi(x1.x) + cw2[1] * bfhi(x2.x) + cw3[1] * bfhi(x3.x);
;                     float v2 = cbv[2] + cw0[2] * bflo(x0.y) + cw1[2] * bflo(x1.y) + cw2[2] * bflo(x2.y) + cw3[2] * bflo(x3.y);
;                     float v3 = cbv[3] + cw0[3] * bfhi(x0.y) + cw1[3] * bfhi(x1.y) + cw2[3] * bfhi(x2.y) + cw3[3] * bfhi(x3.y);
;                     val[j][0] = siluf_(v0); val[j][1] = siluf_(v1); val[j][2] = siluf_(v2); val[j][3] = siluf_(v3); }
;                 const int lb = rg * 32 + seg * 8;
;                 if (kind != 0) { LAS bf16_t* rm = (kind == 1 ? BMm : CM) + lb * SLD + n4;
; #pragma unroll
;                     for (int j = 0; j < 8; ++j) { u32x2 o; o.x = cvt_pk_bf16(val[j][0], val[j][1]); o.y = cvt_pk_bf16(val[j][2], val[j][3]); *(LAS u32x2*)(rm + j * SLD) = o; } }
	v_lshlrev_b32_e32 v198, 16, v84
	v_and_b32_e32 v199, 0xffff0000, v84
	v_lshlrev_b32_e32 v200, 16, v85
	v_and_b32_e32 v201, 0xffff0000, v85
	v_pk_fma_f32 v[44:45], v[48:49], v[198:199], v[64:65]
	v_pk_fma_f32 v[46:47], v[50:51], v[200:201], v[66:67]
	v_pk_fma_f32 v[40:41], v[52:53], v[198:199], v[40:41]
	v_pk_fma_f32 v[42:43], v[54:55], v[200:201], v[42:43]
	v_pk_fma_f32 v[36:37], v[56:57], v[198:199], v[36:37]
	v_pk_fma_f32 v[38:39], v[58:59], v[200:201], v[38:39]
	v_pk_fma_f32 v[32:33], v[60:61], v[198:199], v[32:33]
	v_pk_fma_f32 v[34:35], v[62:63], v[200:201], v[34:35]
	s_waitcnt vmcnt(8)
	v_lshlrev_b32_e32 v194, 16, v82
	v_and_b32_e32 v195, 0xffff0000, v82
	v_lshlrev_b32_e32 v196, 16, v83
	v_and_b32_e32 v197, 0xffff0000, v83
	v_pk_fma_f32 v[44:45], v[52:53], v[194:195], v[44:45]
	v_pk_fma_f32 v[46:47], v[54:55], v[196:197], v[46:47]
	v_pk_fma_f32 v[40:41], v[56:57], v[194:195], v[40:41]
	v_pk_fma_f32 v[42:43], v[58:59], v[196:197], v[42:43]
	v_pk_fma_f32 v[36:37], v[60:61], v[194:195], v[36:37]
	v_pk_fma_f32 v[38:39], v[62:63], v[196:197], v[38:39]
	s_waitcnt vmcnt(7)
	v_lshlrev_b32_e32 v198, 16, v80
	v_and_b32_e32 v199, 0xffff0000, v80
	v_lshlrev_b32_e32 v200, 16, v81
	v_and_b32_e32 v201, 0xffff0000, v81
	v_pk_fma_f32 v[44:45], v[56:57], v[198:199], v[44:45]
	v_pk_fma_f32 v[46:47], v[58:59], v[200:201], v[46:47]
	v_pk_fma_f32 v[40:41], v[60:61], v[198:199], v[40:41]
	v_pk_fma_f32 v[42:43], v[62:63], v[200:201], v[42:43]
	s_waitcnt vmcnt(6)
	v_lshlrev_b32_e32 v194, 16, v78
	v_and_b32_e32 v195, 0xffff0000, v78
	v_lshlrev_b32_e32 v196, 16, v79
	v_and_b32_e32 v197, 0xffff0000, v79
	v_pk_fma_f32 v[44:45], v[60:61], v[194:195], v[44:45]
	v_pk_fma_f32 v[46:47], v[62:63], v[196:197], v[46:47]
	v_pk_mul_f32 v[202:203], v[16:17], v[214:215]
	v_pk_mul_f32 v[204:205], v[18:19], v[214:215]
	v_exp_f32_e32 v202, v202
	v_exp_f32_e32 v203, v203
	v_exp_f32_e32 v204, v204
	v_exp_f32_e32 v205, v205
	v_pk_add_f32 v[202:203], v[202:203], v[216:217]
	v_pk_add_f32 v[204:205], v[204:205], v[216:217]
	v_rcp_f32_e32 v202, v202
	v_rcp_f32_e32 v203, v203
	v_rcp_f32_e32 v204, v204
	v_rcp_f32_e32 v205, v205
	v_pk_mul_f32 v[16:17], v[16:17], v[202:203]
	v_pk_mul_f32 v[18:19], v[18:19], v[204:205]
	v_pk_mul_f32 v[202:203], v[20:21], v[214:215]
	v_pk_mul_f32 v[204:205], v[22:23], v[214:215]
	v_exp_f32_e32 v202, v202
	v_exp_f32_e32 v203, v203
	v_exp_f32_e32 v204, v204
	v_exp_f32_e32 v205, v205
	v_pk_add_f32 v[202:203], v[202:203], v[216:217]
	v_pk_add_f32 v[204:205], v[204:205], v[216:217]
	v_rcp_f32_e32 v202, v202
	v_rcp_f32_e32 v203, v203
	v_rcp_f32_e32 v204, v204
	v_rcp_f32_e32 v205, v205
	v_pk_mul_f32 v[20:21], v[20:21], v[202:203]
	v_pk_mul_f32 v[22:23], v[22:23], v[204:205]
	v_pk_mul_f32 v[202:203], v[24:25], v[214:215]
	v_pk_mul_f32 v[204:205], v[26:27], v[214:215]
	v_exp_f32_e32 v202, v202
	v_exp_f32_e32 v203, v203
	v_exp_f32_e32 v204, v204
	v_exp_f32_e32 v205, v205
	v_pk_add_f32 v[202:203], v[202:203], v[216:217]
	v_pk_add_f32 v[204:205], v[204:205], v[216:217]
	v_rcp_f32_e32 v202, v202
	v_rcp_f32_e32 v203, v203
	v_rcp_f32_e32 v204, v204
	v_rcp_f32_e32 v205, v205
	v_pk_mul_f32 v[24:25], v[24:25], v[202:203]
	v_pk_mul_f32 v[26:27], v[26:27], v[204:205]
	v_pk_mul_f32 v[202:203], v[28:29], v[214:215]
	v_pk_mul_f32 v[204:205], v[30:31], v[214:215]
	v_exp_f32_e32 v202, v202
	v_exp_f32_e32 v203, v203
	v_exp_f32_e32 v204, v204
	v_exp_f32_e32 v205, v205
	v_pk_add_f32 v[202:203], v[202:203], v[216:217]
	v_pk_add_f32 v[204:205], v[204:205], v[216:217]
	v_rcp_f32_e32 v202, v202
	v_rcp_f32_e32 v203, v203
	v_rcp_f32_e32 v204, v204
	v_rcp_f32_e32 v205, v205
	v_pk_mul_f32 v[28:29], v[28:29], v[202:203]
	v_pk_mul_f32 v[30:31], v[30:31], v[204:205]
	v_pk_mul_f32 v[202:203], v[32:33], v[214:215]
	v_pk_mul_f32 v[204:205], v[34:35], v[214:215]
	v_exp_f32_e32 v202, v202
	v_exp_f32_e32 v203, v203
	v_exp_f32_e32 v204, v204
	v_exp_f32_e32 v205, v205
	v_pk_add_f32 v[202:203], v[202:203], v[216:217]
	v_pk_add_f32 v[204:205], v[204:205], v[216:217]
	v_rcp_f32_e32 v202, v202
	v_rcp_f32_e32 v203, v203
	v_rcp_f32_e32 v204, v204
	v_rcp_f32_e32 v205, v205
	v_pk_mul_f32 v[32:33], v[32:33], v[202:203]
	v_pk_mul_f32 v[34:35], v[34:35], v[204:205]
	v_pk_mul_f32 v[202:203], v[36:37], v[214:215]
	v_pk_mul_f32 v[204:205], v[38:39], v[214:215]
	v_exp_f32_e32 v202, v202
	v_exp_f32_e32 v203, v203
	v_exp_f32_e32 v204, v204
	v_exp_f32_e32 v205, v205
	v_pk_add_f32 v[202:203], v[202:203], v[216:217]
	v_pk_add_f32 v[204:205], v[204:205], v[216:217]
	v_rcp_f32_e32 v202, v202
	v_rcp_f32_e32 v203, v203
	v_rcp_f32_e32 v204, v204
	v_rcp_f32_e32 v205, v205
	v_pk_mul_f32 v[36:37], v[36:37], v[202:203]
	v_pk_mul_f32 v[38:39], v[38:39], v[204:205]
	v_pk_mul_f32 v[202:203], v[40:41], v[214:215]
	v_pk_mul_f32 v[204:205], v[42:43], v[214:215]
	v_exp_f32_e32 v202, v202
	v_exp_f32_e32 v203, v203
	v_exp_f32_e32 v204, v204
	v_exp_f32_e32 v205, v205
	v_pk_add_f32 v[202:203], v[202:203], v[216:217]
	v_pk_add_f32 v[204:205], v[204:205], v[216:217]
	v_rcp_f32_e32 v202, v202
	v_rcp_f32_e32 v203, v203
	v_rcp_f32_e32 v204, v204
	v_rcp_f32_e32 v205, v205
	v_pk_mul_f32 v[40:41], v[40:41], v[202:203]
	v_pk_mul_f32 v[42:43], v[42:43], v[204:205]
	v_pk_mul_f32 v[202:203], v[44:45], v[214:215]
	v_pk_mul_f32 v[204:205], v[46:47], v[214:215]
	v_exp_f32_e32 v202, v202
	v_exp_f32_e32 v203, v203
	v_exp_f32_e32 v204, v204
	v_exp_f32_e32 v205, v205
	v_pk_add_f32 v[202:203], v[202:203], v[216:217]
	v_pk_add_f32 v[204:205], v[204:205], v[216:217]
	v_rcp_f32_e32 v202, v202
	v_rcp_f32_e32 v203, v203
	v_rcp_f32_e32 v204, v204
	v_rcp_f32_e32 v205, v205
	v_pk_mul_f32 v[44:45], v[44:45], v[202:203]
	v_pk_mul_f32 v[46:47], v[46:47], v[204:205]
	s_and_saveexec_b64 vcc, s[38:39]
	s_cbranch_execz .Lcv_rm_3
	v_cvt_pk_bf16_f32 v194, v16, v17
	v_cvt_pk_bf16_f32 v195, v18, v19
	ds_write_b64 v187, v[194:195] offset:6528
	v_cvt_pk_bf16_f32 v196, v20, v21
	v_cvt_pk_bf16_f32 v197, v22, v23
	ds_write_b64 v187, v[196:197] offset:6800
	v_cvt_pk_bf16_f32 v194, v24, v25
	v_cvt_pk_bf16_f32 v195, v26, v27
	ds_write_b64 v187, v[194:195] offset:7072
	v_cvt_pk_bf16_f32 v196, v28, v29
	v_cvt_pk_bf16_f32 v197, v30, v31
	ds_write_b64 v187, v[196:197] offset:7344
	v_cvt_pk_bf16_f32 v194, v32, v33
	v_cvt_pk_bf16_f32 v195, v34, v35
	ds_write_b64 v187, v[194:195] offset:7616
	v_cvt_pk_bf16_f32 v196, v36, v37
	v_cvt_pk_bf16_f32 v197, v38, v39
	ds_write_b64 v187, v[196:197] offset:7888
	v_cvt_pk_bf16_f32 v194, v40, v41
	v_cvt_pk_bf16_f32 v195, v42, v43
	ds_write_b64 v187, v[194:195] offset:8160
	v_cvt_pk_bf16_f32 v196, v44, v45
	v_cvt_pk_bf16_f32 v197, v46, v47
	ds_write_b64 v187, v[196:197] offset:8432
; __device__ __forceinline__ unsigned cvt_pk_bf16(float lo, float hi) { unsigned r; asm volatile("v_cvt_pk_bf16_f32 %0, %1, %2" : "=v"(r) : "v"(lo), "v"(hi)); return r; }
; #define LAS __attribute__((address_space(3)))
; __device__ __forceinline__ void ssd_item(const Params& p, LAS unsigned char* lds, int bl, int head, int dry) {
;     ...
;                 if (kind != 2) { LAS float* sc = (kind == 0 ? fdt : fwl) + lb; LAS bf16_t* tp = (kind == 0 ? XT : BT) + n4 * SLD + lb;
;                     float scl[8];
; #pragma unroll
;                     for (int j = 0; j < 8; ++j) scl[j] = sc[j];
; #pragma unroll
;                     for (int e = 0; e < 4; ++e) { u32x4 o; o.x = cvt_pk_bf16(val[0][e] * scl[0], val[1][e] * scl[1]); o.y = cvt_pk_bf16(val[2][e] * scl[2], val[3][e] * scl[3]);
;                         o.z = cvt_pk_bf16(val[4][e] * scl[4], val[5][e] * scl[5]); o.w = cvt_pk_bf16(val[6][e] * scl[6], val[7][e] * scl[7]); *(LAS u32x4*)(tp + e * SLD) = o; } }
.Lcv_rm_3:
	s_or_b64 exec, exec, vcc
	s_and_saveexec_b64 vcc, s[34:35]
	s_cbranch_execz .Lcv_tr_3
	ds_read_b128 v[206:209], v218 offset:96
	ds_read_b128 v[210:213], v218 offset:112
	s_waitcnt lgkmcnt(0)
	v_pk_mul_f32 v[16:17], v[16:17], v[206:207] op_sel_hi:[1,0]
	v_pk_mul_f32 v[18:19], v[18:19], v[206:207] op_sel_hi:[1,0]
	v_pk_mul_f32 v[20:21], v[20:21], v[206:207] op_sel:[0,1] op_sel_hi:[1,1]
	v_pk_mul_f32 v[22:23], v[22:23], v[206:207] op_sel:[0,1] op_sel_hi:[1,1]
	v_pk_mul_f32 v[24:25], v[24:25], v[208:209] op_sel_hi:[1,0]
	v_pk_mul_f32 v[26:27], v[26:27], v[208:209] op_sel_hi:[1,0]
	v_pk_mul_f32 v[28:29], v[28:29], v[208:209] op_sel:[0,1] op_sel_hi:[1,1]
	v_pk_mul_f32 v[30:31], v[30:31], v[208:209] op_sel:[0,1] op_sel_hi:[1,1]
	v_pk_mul_f32 v[32:33], v[32:33], v[210:211] op_sel_hi:[1,0]
	v_pk_mul_f32 v[34:35], v[34:35], v[210:211] op_sel_hi:[1,0]
	v_pk_mul_f32 v[36:37], v[36:37], v[210:211] op_sel:[0,1] op_sel_hi:[1,1]
	v_pk_mul_f32 v[38:39], v[38:39], v[210:211] op_sel:[0,1] op_sel_hi:[1,1]
	v_pk_mul_f32 v[40:41], v[40:41], v[212:213] op_sel_hi:[1,0]
	v_pk_mul_f32 v[42:43], v[42:43], v[212:213] op_sel_hi:[1,0]
	v_pk_mul_f32 v[44:45], v[44:45], v[212:213] op_sel:[0,1] op_sel_hi:[1,1]
	v_pk_mul_f32 v[46:47], v[46:47], v[212:213] op_sel:[0,1] op_sel_hi:[1,1]
	v_cvt_pk_bf16_f32 v236, v16, v20
	v_cvt_pk_bf16_f32 v237, v24, v28
	v_cvt_pk_bf16_f32 v238, v32, v36
	v_cvt_pk_bf16_f32 v239, v40, v44
	ds_write_b128 v178, v[236:239] offset:48
	v_cvt_pk_bf16_f32 v198, v17, v21
	v_cvt_pk_bf16_f32 v199, v25, v29
	v_cvt_pk_bf16_f32 v200, v33, v37
	v_cvt_pk_bf16_f32 v201, v41, v45
	ds_write_b128 v178, v[198:201] offset:320
	v_cvt_pk_bf16_f32 v236, v18, v22
	v_cvt_pk_bf16_f32 v237, v26, v30
	v_cvt_pk_bf16_f32 v238, v34, v38
	v_cvt_pk_bf16_f32 v239, v42, v46
	ds_write_b128 v178, v[236:239] offset:592
	v_cvt_pk_bf16_f32 v198, v19, v23
	v_cvt_pk_bf16_f32 v199, v27, v31
	v_cvt_pk_bf16_f32 v200, v35, v39
	v_cvt_pk_bf16_f32 v201, v43, v47
	ds_write_b128 v178, v[198:201] offset:864
